# out-proj unrolled K-loop: the eight global loads of each half-step hoisted from the end of the half-step to right behind the staging writes (two shared quads renamed to free registers)
# speedup vs baseline: 1.0654x; 1.0003x over previous
; #define G_LOAD(AG, BG, kt, RA, RB) do { const int k0_ = (kt) * 64; int ac_ = k0_; if (g.remap) ac_ = k0_ < 512 ? k0_ : (k0_ < 1024 ? g.seg2 + k0_ - 512 : 2304 + k0_ - 1024); \
;     _Pragma("unroll") for (int i = 0; i < 4; ++i) { RA[i] = *(const u32x4*)(AG + (size_t)(64 * i) * g.lda + ac_); RB[i] = *(const u32x4*)(BG + (size_t)(64 * i) * g.K + k0_); } } while (0)
; #define G_WRITE(buf, RA, RB) do { _Pragma("unroll") for (int i = 0; i < 4; ++i) { *(u32x4*)(lds + (buf) * 65536 + i * 8192 + soff) = RA[i]; *(u32x4*)(lds + (buf) * 65536 + 32768 + i * 8192 + soff) = RB[i]; } } while (0)
; template <int EPI>
; DI void gemm_phase(char* lds, const Params& p, const GemmDesc g, int layer) {
;     ...
;     for (int kt = 0; kt < nk; kt += 2) {
;       const bool last = kt + 2 >= nk;
;       G_WRITE(1, ra0, rb0);
;       if (!last) G_LOAD(Ag, Bg, kt + 2, ra0, rb0); else if (has_next) G_LOAD(Agn, Bgn, 0, ra0, rb0);
;       G_COMPUTE(0);
;       __syncthreads();
;       if (!last || has_next) G_WRITE(0, ra0, rb0);
;       if (!last) G_LOAD(Ag, Bg, kt + 3, ra0, rb0); else if (has_next) G_LOAD(Agn, Bgn, 1, ra0, rb0);
;       G_COMPUTE(1);
;       __syncthreads();
.LBB0_118:
	s_waitcnt vmcnt(7)
	ds_write_b128 v202, v[134:137]
	s_waitcnt vmcnt(6)
	ds_write_b128 v203, v[130:133]
	s_waitcnt vmcnt(5)
	ds_write_b128 v202, v[138:141] offset:8192
	s_waitcnt vmcnt(4)
	ds_write_b128 v203, v[142:145] offset:8192
	s_waitcnt vmcnt(3)
	ds_write_b128 v202, v[146:149] offset:16384
	s_waitcnt vmcnt(2)
	ds_write_b128 v203, v[150:153] offset:16384
	s_waitcnt vmcnt(1)
	ds_write_b128 v202, v[154:157] offset:24576
	s_waitcnt vmcnt(0)
	ds_write_b128 v203, v[158:161] offset:24576
	s_waitcnt lgkmcnt(8)
	ds_read_b128 v[2:5], v205 offset:32768
	ds_read_b128 v[6:9], v204
	ds_read_b128 v[10:13], v204 offset:4096
	ds_read_b128 v[14:17], v205 offset:36864
	s_mov_b32 s0, 0x28000
	s_mov_b32 s1, 0x50000
	s_waitcnt lgkmcnt(2)
	v_mfma_f32_32x32x16_bf16 v[114:129], v[2:5], v[6:9], 0
	v_lshl_add_u32 v0, s84, 8, v200
	s_waitcnt lgkmcnt(1)
	v_mfma_f32_32x32x16_bf16 v[50:65], v[2:5], v[10:13], 0
	s_waitcnt lgkmcnt(0)
	v_mfma_f32_32x32x16_bf16 v[98:113], v[14:17], v[6:9], 0
	v_mfma_f32_32x32x16_bf16 v[34:49], v[14:17], v[10:13], 0
	ds_read_b128 v[2:5], v205 offset:40960
	ds_read_b128 v[14:17], v205 offset:45056
	ds_read_b128 v[130:133], v207 offset:32768
	ds_read_b128 v[134:137], v206
	ds_read_b128 v[138:141], v206 offset:4096
	ds_read_b128 v[142:145], v207 offset:36864
	s_waitcnt lgkmcnt(5)
	v_mfma_f32_32x32x16_bf16 v[82:97], v[2:5], v[6:9], 0
	v_mfma_f32_32x32x16_bf16 v[18:33], v[2:5], v[10:13], 0
	s_waitcnt lgkmcnt(4)
	v_mfma_f32_32x32x16_bf16 v[66:81], v[14:17], v[6:9], 0
	v_mfma_f32_32x32x16_bf16 v[2:17], v[14:17], v[10:13], 0
	s_waitcnt lgkmcnt(2)
	v_mfma_f32_32x32x16_bf16 v[114:129], v[130:133], v[134:137], v[114:129]
	s_waitcnt lgkmcnt(1)
	v_mfma_f32_32x32x16_bf16 v[50:65], v[130:133], v[138:141], v[50:65]
	s_waitcnt lgkmcnt(0)
	v_mfma_f32_32x32x16_bf16 v[98:113], v[142:145], v[134:137], v[98:113]
	v_mfma_f32_32x32x16_bf16 v[34:49], v[142:145], v[138:141], v[34:49]
	ds_read_b128 v[130:133], v207 offset:40960
	ds_read_b128 v[142:145], v207 offset:45056
	s_waitcnt lgkmcnt(1)
	v_mfma_f32_32x32x16_bf16 v[82:97], v[130:133], v[134:137], v[82:97]
	v_mfma_f32_32x32x16_bf16 v[18:33], v[130:133], v[138:141], v[18:33]
	s_waitcnt lgkmcnt(0)
	v_mfma_f32_32x32x16_bf16 v[66:81], v[142:145], v[134:137], v[66:81]
	v_mfma_f32_32x32x16_bf16 v[2:17], v[142:145], v[138:141], v[2:17]
	ds_read_b128 v[130:133], v209 offset:32768
	ds_read_b128 v[134:137], v208
	ds_read_b128 v[138:141], v208 offset:4096
	ds_read_b128 v[142:145], v209 offset:36864
	s_waitcnt lgkmcnt(2)
	v_mfma_f32_32x32x16_bf16 v[114:129], v[130:133], v[134:137], v[114:129]
	s_waitcnt lgkmcnt(1)
	v_mfma_f32_32x32x16_bf16 v[50:65], v[130:133], v[138:141], v[50:65]
	s_waitcnt lgkmcnt(0)
	v_mfma_f32_32x32x16_bf16 v[98:113], v[142:145], v[134:137], v[98:113]
	v_mfma_f32_32x32x16_bf16 v[34:49], v[142:145], v[138:141], v[34:49]
	ds_read_b128 v[130:133], v209 offset:40960
	ds_read_b128 v[142:145], v209 offset:45056
	s_waitcnt lgkmcnt(1)
	v_mfma_f32_32x32x16_bf16 v[82:97], v[130:133], v[134:137], v[82:97]
	v_mfma_f32_32x32x16_bf16 v[18:33], v[130:133], v[138:141], v[18:33]
	s_waitcnt lgkmcnt(0)
	v_mfma_f32_32x32x16_bf16 v[66:81], v[142:145], v[134:137], v[66:81]
	v_mfma_f32_32x32x16_bf16 v[2:17], v[142:145], v[138:141], v[2:17]
	ds_read_b128 v[130:133], v211 offset:32768
	ds_read_b128 v[136:139], v210
	ds_read_b128 v[148:151], v210 offset:4096
	ds_read_b128 v[144:147], v211 offset:36864
	ds_read_b128 v[156:159], v211 offset:40960
	ds_read_b128 v[188:191], v211 offset:45056
	global_load_dwordx4 v[152:155], v[168:169], off offset:256
	global_load_dwordx4 v[172:175], v[170:171], off offset:256
	s_waitcnt lgkmcnt(4)
	v_mfma_f32_32x32x16_bf16 v[114:129], v[130:133], v[136:139], v[114:129]
	s_waitcnt lgkmcnt(3)
	v_mfma_f32_32x32x16_bf16 v[50:65], v[130:133], v[148:151], v[50:65]
	v_add_co_u32_e32 v130, vcc, s34, v168
	s_nop 1
	v_addc_co_u32_e32 v131, vcc, 0, v169, vcc
	v_add_co_u32_e32 v142, vcc, s0, v170
	s_mov_b32 s0, 0xf0000
	s_nop 0
	v_addc_co_u32_e32 v143, vcc, 0, v171, vcc
	v_add_co_u32_e32 v132, vcc, s0, v168
	s_waitcnt lgkmcnt(2)
	v_mfma_f32_32x32x16_bf16 v[98:113], v[144:147], v[136:139], v[98:113]
	v_addc_co_u32_e32 v133, vcc, 0, v169, vcc
	global_load_dwordx4 v[176:179], v[130:131], off offset:256
	global_load_dwordx4 v[184:187], v[132:133], off offset:256
	global_load_dwordx4 v[180:183], v[142:143], off offset:256
	v_mfma_f32_32x32x16_bf16 v[34:49], v[144:147], v[148:151], v[34:49]
	v_add_co_u32_e32 v146, vcc, s1, v170
	s_mov_b32 s1, 0x168000
	s_nop 0
	v_addc_co_u32_e32 v147, vcc, 0, v171, vcc
	v_add_co_u32_e32 v134, vcc, s1, v168
	s_waitcnt lgkmcnt(1)
	v_mfma_f32_32x32x16_bf16 v[82:97], v[156:159], v[136:139], v[82:97]
	v_addc_co_u32_e32 v135, vcc, 0, v169, vcc
	global_load_dwordx4 v[192:195], v[146:147], off offset:256
	global_load_dwordx4 v[196:199], v[134:135], off offset:256
	v_mfma_f32_32x32x16_bf16 v[18:33], v[156:159], v[148:151], v[18:33]
	v_add_co_u32_e32 v158, vcc, s34, v170
	s_nop 1
	v_addc_co_u32_e32 v159, vcc, 0, v171, vcc
	s_waitcnt lgkmcnt(0)
	v_mfma_f32_32x32x16_bf16 v[66:81], v[188:191], v[136:139], v[66:81]
	global_load_dwordx4 v[136:139], v[158:159], off offset:256
	s_barrier
; #define G_LOAD(AG, BG, kt, RA, RB) do { const int k0_ = (kt) * 64; int ac_ = k0_; if (g.remap) ac_ = k0_ < 512 ? k0_ : (k0_ < 1024 ? g.seg2 + k0_ - 512 : 2304 + k0_ - 1024); \
;     _Pragma("unroll") for (int i = 0; i < 4; ++i) { RA[i] = *(const u32x4*)(AG + (size_t)(64 * i) * g.lda + ac_); RB[i] = *(const u32x4*)(BG + (size_t)(64 * i) * g.K + k0_); } } while (0)
; #define G_WRITE(buf, RA, RB) do { _Pragma("unroll") for (int i = 0; i < 4; ++i) { *(u32x4*)(lds + (buf) * 65536 + i * 8192 + soff) = RA[i]; *(u32x4*)(lds + (buf) * 65536 + 32768 + i * 8192 + soff) = RB[i]; } } while (0)
; template <int EPI>
; DI void gemm_phase(char* lds, const Params& p, const GemmDesc g, int layer) {
;     ...
;     for (int kt = 0; kt < nk; kt += 2) {
;       const bool last = kt + 2 >= nk;
;       G_WRITE(1, ra0, rb0);
;       if (!last) G_LOAD(Ag, Bg, kt + 2, ra0, rb0); else if (has_next) G_LOAD(Agn, Bgn, 0, ra0, rb0);
;       G_COMPUTE(0);
;       __syncthreads();
;       if (!last || has_next) G_WRITE(0, ra0, rb0);
;       if (!last) G_LOAD(Ag, Bg, kt + 3, ra0, rb0); else if (has_next) G_LOAD(Agn, Bgn, 1, ra0, rb0);
;       G_COMPUTE(1);
;       __syncthreads();
	s_waitcnt vmcnt(7)
	ds_write_b128 v201, v[152:155]
	s_waitcnt vmcnt(6)
	ds_write_b128 v201, v[172:175] offset:32768
	s_waitcnt vmcnt(5)
	ds_write_b128 v201, v[176:179] offset:8192
	s_waitcnt vmcnt(3)
	ds_write_b128 v201, v[180:183] offset:40960
	ds_write_b128 v201, v[184:187] offset:16384
	s_waitcnt vmcnt(2)
	ds_write_b128 v201, v[192:195] offset:49152
	s_waitcnt vmcnt(1)
	ds_write_b128 v201, v[196:199] offset:24576
	s_waitcnt vmcnt(0)
	ds_write_b128 v201, v[136:139] offset:57344
	global_load_dwordx4 v[236:239], v[134:135], off offset:384
	global_load_dwordx4 v[176:179], v[168:169], off offset:384
	global_load_dwordx4 v[180:183], v[170:171], off offset:384
	global_load_dwordx4 v[184:187], v[130:131], off offset:384
	global_load_dwordx4 v[240:243], v[142:143], off offset:384
	global_load_dwordx4 v[192:195], v[132:133], off offset:384
	global_load_dwordx4 v[196:199], v[146:147], off offset:384
	global_load_dwordx4 v[244:247], v[158:159], off offset:384
	v_mfma_f32_32x32x16_bf16 v[2:17], v[188:191], v[148:151], v[2:17]
	ds_read_b128 v[136:139], v223
	ds_read_b128 v[148:151], v222
	ds_read_b128 v[152:155], v222 offset:4096
	ds_read_b128 v[172:175], v223 offset:4096
	s_waitcnt lgkmcnt(2)
	v_mfma_f32_32x32x16_bf16 v[114:129], v[136:139], v[148:151], v[114:129]
	s_waitcnt lgkmcnt(1)
	v_mfma_f32_32x32x16_bf16 v[50:65], v[136:139], v[152:155], v[50:65]
	s_waitcnt lgkmcnt(0)
	v_mfma_f32_32x32x16_bf16 v[98:113], v[172:175], v[148:151], v[98:113]
	v_mfma_f32_32x32x16_bf16 v[34:49], v[172:175], v[152:155], v[34:49]
	ds_read_b128 v[136:139], v223 offset:8192
	ds_read_b128 v[172:175], v223 offset:12288
	s_waitcnt lgkmcnt(1)
	v_mfma_f32_32x32x16_bf16 v[82:97], v[136:139], v[148:151], v[82:97]
	v_mfma_f32_32x32x16_bf16 v[18:33], v[136:139], v[152:155], v[18:33]
	s_waitcnt lgkmcnt(0)
	v_mfma_f32_32x32x16_bf16 v[66:81], v[172:175], v[148:151], v[66:81]
	v_mfma_f32_32x32x16_bf16 v[2:17], v[172:175], v[152:155], v[2:17]
	ds_read_b128 v[136:139], v225
	ds_read_b128 v[148:151], v224
	ds_read_b128 v[152:155], v224 offset:4096
	ds_read_b128 v[172:175], v225 offset:4096
	s_waitcnt lgkmcnt(2)
	v_mfma_f32_32x32x16_bf16 v[114:129], v[136:139], v[148:151], v[114:129]
	s_waitcnt lgkmcnt(1)
	v_mfma_f32_32x32x16_bf16 v[50:65], v[136:139], v[152:155], v[50:65]
	s_waitcnt lgkmcnt(0)
	v_mfma_f32_32x32x16_bf16 v[98:113], v[172:175], v[148:151], v[98:113]
	v_mfma_f32_32x32x16_bf16 v[34:49], v[172:175], v[152:155], v[34:49]
	ds_read_b128 v[136:139], v225 offset:8192
	ds_read_b128 v[172:175], v225 offset:12288
	s_waitcnt lgkmcnt(1)
	v_mfma_f32_32x32x16_bf16 v[82:97], v[136:139], v[148:151], v[82:97]
	v_mfma_f32_32x32x16_bf16 v[18:33], v[136:139], v[152:155], v[18:33]
	s_waitcnt lgkmcnt(0)
	v_mfma_f32_32x32x16_bf16 v[66:81], v[172:175], v[148:151], v[66:81]
	v_mfma_f32_32x32x16_bf16 v[2:17], v[172:175], v[152:155], v[2:17]
	ds_read_b128 v[136:139], v227
	ds_read_b128 v[148:151], v226
	ds_read_b128 v[152:155], v226 offset:4096
	ds_read_b128 v[172:175], v227 offset:4096
	s_waitcnt lgkmcnt(2)
	v_mfma_f32_32x32x16_bf16 v[114:129], v[136:139], v[148:151], v[114:129]
	s_waitcnt lgkmcnt(1)
	v_mfma_f32_32x32x16_bf16 v[50:65], v[136:139], v[152:155], v[50:65]
	s_waitcnt lgkmcnt(0)
	v_mfma_f32_32x32x16_bf16 v[98:113], v[172:175], v[148:151], v[98:113]
	v_mfma_f32_32x32x16_bf16 v[34:49], v[172:175], v[152:155], v[34:49]
	ds_read_b128 v[136:139], v227 offset:8192
	ds_read_b128 v[172:175], v227 offset:12288
	s_waitcnt lgkmcnt(1)
	v_mfma_f32_32x32x16_bf16 v[82:97], v[136:139], v[148:151], v[82:97]
	v_mfma_f32_32x32x16_bf16 v[18:33], v[136:139], v[152:155], v[18:33]
	s_waitcnt lgkmcnt(0)
	v_mfma_f32_32x32x16_bf16 v[66:81], v[172:175], v[148:151], v[66:81]
	v_mfma_f32_32x32x16_bf16 v[2:17], v[172:175], v[152:155], v[2:17]
	ds_read_b128 v[136:139], v229
	ds_read_b128 v[148:151], v228
	ds_read_b128 v[152:155], v228 offset:4096
	ds_read_b128 v[172:175], v229 offset:4096
	s_waitcnt lgkmcnt(2)
	v_mfma_f32_32x32x16_bf16 v[114:129], v[136:139], v[148:151], v[114:129]
	s_waitcnt lgkmcnt(1)
	v_mfma_f32_32x32x16_bf16 v[50:65], v[136:139], v[152:155], v[50:65]
	s_waitcnt lgkmcnt(0)
	v_mfma_f32_32x32x16_bf16 v[98:113], v[172:175], v[148:151], v[98:113]
	v_mfma_f32_32x32x16_bf16 v[34:49], v[172:175], v[152:155], v[34:49]
	ds_read_b128 v[136:139], v229 offset:8192
	ds_read_b128 v[172:175], v229 offset:12288
	s_waitcnt lgkmcnt(1)
	v_mfma_f32_32x32x16_bf16 v[82:97], v[136:139], v[148:151], v[82:97]
	v_mfma_f32_32x32x16_bf16 v[18:33], v[136:139], v[152:155], v[18:33]
	s_waitcnt lgkmcnt(0)
	v_mfma_f32_32x32x16_bf16 v[66:81], v[172:175], v[148:151], v[66:81]
	s_barrier
; #define G_LOAD(AG, BG, kt, RA, RB) do { const int k0_ = (kt) * 64; int ac_ = k0_; if (g.remap) ac_ = k0_ < 512 ? k0_ : (k0_ < 1024 ? g.seg2 + k0_ - 512 : 2304 + k0_ - 1024); \
;     _Pragma("unroll") for (int i = 0; i < 4; ++i) { RA[i] = *(const u32x4*)(AG + (size_t)(64 * i) * g.lda + ac_); RB[i] = *(const u32x4*)(BG + (size_t)(64 * i) * g.K + k0_); } } while (0)
; #define G_WRITE(buf, RA, RB) do { _Pragma("unroll") for (int i = 0; i < 4; ++i) { *(u32x4*)(lds + (buf) * 65536 + i * 8192 + soff) = RA[i]; *(u32x4*)(lds + (buf) * 65536 + 32768 + i * 8192 + soff) = RB[i]; } } while (0)
; template <int EPI>
; DI void gemm_phase(char* lds, const Params& p, const GemmDesc g, int layer) {
;     ...
;     for (int kt = 0; kt < nk; kt += 2) {
;       const bool last = kt + 2 >= nk;
;       G_WRITE(1, ra0, rb0);
;       if (!last) G_LOAD(Ag, Bg, kt + 2, ra0, rb0); else if (has_next) G_LOAD(Agn, Bgn, 0, ra0, rb0);
;       G_COMPUTE(0);
;       __syncthreads();
;       if (!last || has_next) G_WRITE(0, ra0, rb0);
;       if (!last) G_LOAD(Ag, Bg, kt + 3, ra0, rb0); else if (has_next) G_LOAD(Agn, Bgn, 1, ra0, rb0);
;       G_COMPUTE(1);
;       __syncthreads();
	s_waitcnt vmcnt(6)
	ds_write_b128 v202, v[176:179]
	s_waitcnt vmcnt(5)
	ds_write_b128 v203, v[180:183]
	s_waitcnt vmcnt(4)
	ds_write_b128 v202, v[184:187] offset:8192
	s_waitcnt vmcnt(3)
	ds_write_b128 v203, v[240:243] offset:8192
	s_waitcnt vmcnt(2)
	ds_write_b128 v202, v[192:195] offset:16384
	s_waitcnt vmcnt(1)
	ds_write_b128 v203, v[196:199] offset:16384
	ds_write_b128 v202, v[236:239] offset:24576
	s_waitcnt vmcnt(0)
	ds_write_b128 v203, v[244:247] offset:24576
	global_load_dwordx4 v[236:239], v[168:169], off offset:512
	global_load_dwordx4 v[176:179], v[170:171], off offset:512
	global_load_dwordx4 v[180:183], v[130:131], off offset:512
	global_load_dwordx4 v[184:187], v[142:143], off offset:512
	global_load_dwordx4 v[188:191], v[132:133], off offset:512
	global_load_dwordx4 v[192:195], v[146:147], off offset:512
	global_load_dwordx4 v[196:199], v[134:135], off offset:512
	global_load_dwordx4 v[240:243], v[158:159], off offset:512
	v_mfma_f32_32x32x16_bf16 v[2:17], v[172:175], v[152:155], v[2:17]
	ds_read_b128 v[136:139], v205 offset:32768
	ds_read_b128 v[148:151], v204
	ds_read_b128 v[152:155], v204 offset:4096
	ds_read_b128 v[172:175], v205 offset:36864
	s_waitcnt lgkmcnt(2)
	v_mfma_f32_32x32x16_bf16 v[114:129], v[136:139], v[148:151], v[114:129]
	s_waitcnt lgkmcnt(1)
	v_mfma_f32_32x32x16_bf16 v[50:65], v[136:139], v[152:155], v[50:65]
	s_waitcnt lgkmcnt(0)
	v_mfma_f32_32x32x16_bf16 v[98:113], v[172:175], v[148:151], v[98:113]
	v_mfma_f32_32x32x16_bf16 v[34:49], v[172:175], v[152:155], v[34:49]
	ds_read_b128 v[136:139], v205 offset:40960
	ds_read_b128 v[172:175], v205 offset:45056
	s_waitcnt lgkmcnt(1)
	v_mfma_f32_32x32x16_bf16 v[82:97], v[136:139], v[148:151], v[82:97]
	v_mfma_f32_32x32x16_bf16 v[18:33], v[136:139], v[152:155], v[18:33]
	s_waitcnt lgkmcnt(0)
	v_mfma_f32_32x32x16_bf16 v[66:81], v[172:175], v[148:151], v[66:81]
	v_mfma_f32_32x32x16_bf16 v[2:17], v[172:175], v[152:155], v[2:17]
	ds_read_b128 v[136:139], v207 offset:32768
	ds_read_b128 v[148:151], v206
	ds_read_b128 v[152:155], v206 offset:4096
	ds_read_b128 v[172:175], v207 offset:36864
	s_waitcnt lgkmcnt(2)
	v_mfma_f32_32x32x16_bf16 v[114:129], v[136:139], v[148:151], v[114:129]
	s_waitcnt lgkmcnt(1)
	v_mfma_f32_32x32x16_bf16 v[50:65], v[136:139], v[152:155], v[50:65]
	s_waitcnt lgkmcnt(0)
	v_mfma_f32_32x32x16_bf16 v[98:113], v[172:175], v[148:151], v[98:113]
	v_mfma_f32_32x32x16_bf16 v[34:49], v[172:175], v[152:155], v[34:49]
	ds_read_b128 v[136:139], v207 offset:40960
	ds_read_b128 v[172:175], v207 offset:45056
	s_waitcnt lgkmcnt(1)
	v_mfma_f32_32x32x16_bf16 v[82:97], v[136:139], v[148:151], v[82:97]
	v_mfma_f32_32x32x16_bf16 v[18:33], v[136:139], v[152:155], v[18:33]
	s_waitcnt lgkmcnt(0)
	v_mfma_f32_32x32x16_bf16 v[66:81], v[172:175], v[148:151], v[66:81]
	v_mfma_f32_32x32x16_bf16 v[2:17], v[172:175], v[152:155], v[2:17]
	ds_read_b128 v[136:139], v209 offset:32768
	ds_read_b128 v[148:151], v208
	ds_read_b128 v[152:155], v208 offset:4096
	ds_read_b128 v[172:175], v209 offset:36864
	s_waitcnt lgkmcnt(2)
	v_mfma_f32_32x32x16_bf16 v[114:129], v[136:139], v[148:151], v[114:129]
	s_waitcnt lgkmcnt(1)
	v_mfma_f32_32x32x16_bf16 v[50:65], v[136:139], v[152:155], v[50:65]
	s_waitcnt lgkmcnt(0)
	v_mfma_f32_32x32x16_bf16 v[98:113], v[172:175], v[148:151], v[98:113]
	v_mfma_f32_32x32x16_bf16 v[34:49], v[172:175], v[152:155], v[34:49]
	ds_read_b128 v[136:139], v209 offset:40960
	ds_read_b128 v[172:175], v209 offset:45056
	s_waitcnt lgkmcnt(1)
	v_mfma_f32_32x32x16_bf16 v[82:97], v[136:139], v[148:151], v[82:97]
	v_mfma_f32_32x32x16_bf16 v[18:33], v[136:139], v[152:155], v[18:33]
	s_waitcnt lgkmcnt(0)
	v_mfma_f32_32x32x16_bf16 v[66:81], v[172:175], v[148:151], v[66:81]
	v_mfma_f32_32x32x16_bf16 v[2:17], v[172:175], v[152:155], v[2:17]
	ds_read_b128 v[136:139], v211 offset:32768
	ds_read_b128 v[148:151], v210
	ds_read_b128 v[152:155], v210 offset:4096
	ds_read_b128 v[172:175], v211 offset:36864
	s_waitcnt lgkmcnt(2)
	v_mfma_f32_32x32x16_bf16 v[114:129], v[136:139], v[148:151], v[114:129]
	s_waitcnt lgkmcnt(1)
	v_mfma_f32_32x32x16_bf16 v[50:65], v[136:139], v[152:155], v[50:65]
	s_waitcnt lgkmcnt(0)
	v_mfma_f32_32x32x16_bf16 v[98:113], v[172:175], v[148:151], v[98:113]
	v_mfma_f32_32x32x16_bf16 v[34:49], v[172:175], v[152:155], v[34:49]
	ds_read_b128 v[136:139], v211 offset:40960
	ds_read_b128 v[172:175], v211 offset:45056
	s_waitcnt lgkmcnt(1)
	v_mfma_f32_32x32x16_bf16 v[82:97], v[136:139], v[148:151], v[82:97]
	v_mfma_f32_32x32x16_bf16 v[18:33], v[136:139], v[152:155], v[18:33]
	s_waitcnt lgkmcnt(0)
	v_mfma_f32_32x32x16_bf16 v[66:81], v[172:175], v[148:151], v[66:81]
	s_barrier
; #define G_LOAD(AG, BG, kt, RA, RB) do { const int k0_ = (kt) * 64; int ac_ = k0_; if (g.remap) ac_ = k0_ < 512 ? k0_ : (k0_ < 1024 ? g.seg2 + k0_ - 512 : 2304 + k0_ - 1024); \
;     _Pragma("unroll") for (int i = 0; i < 4; ++i) { RA[i] = *(const u32x4*)(AG + (size_t)(64 * i) * g.lda + ac_); RB[i] = *(const u32x4*)(BG + (size_t)(64 * i) * g.K + k0_); } } while (0)
; #define G_WRITE(buf, RA, RB) do { _Pragma("unroll") for (int i = 0; i < 4; ++i) { *(u32x4*)(lds + (buf) * 65536 + i * 8192 + soff) = RA[i]; *(u32x4*)(lds + (buf) * 65536 + 32768 + i * 8192 + soff) = RB[i]; } } while (0)
; template <int EPI>
; DI void gemm_phase(char* lds, const Params& p, const GemmDesc g, int layer) {
;     ...
;     for (int kt = 0; kt < nk; kt += 2) {
;       const bool last = kt + 2 >= nk;
;       G_WRITE(1, ra0, rb0);
;       if (!last) G_LOAD(Ag, Bg, kt + 2, ra0, rb0); else if (has_next) G_LOAD(Agn, Bgn, 0, ra0, rb0);
;       G_COMPUTE(0);
;       __syncthreads();
;       if (!last || has_next) G_WRITE(0, ra0, rb0);
;       if (!last) G_LOAD(Ag, Bg, kt + 3, ra0, rb0); else if (has_next) G_LOAD(Agn, Bgn, 1, ra0, rb0);
;       G_COMPUTE(1);
;       __syncthreads();
	s_waitcnt vmcnt(7)
	ds_write_b128 v201, v[236:239]
	s_waitcnt vmcnt(6)
	ds_write_b128 v201, v[176:179] offset:32768
	s_waitcnt vmcnt(5)
	ds_write_b128 v201, v[180:183] offset:8192
	s_waitcnt vmcnt(4)
	ds_write_b128 v201, v[184:187] offset:40960
	s_waitcnt vmcnt(3)
	ds_write_b128 v201, v[188:191] offset:16384
	s_waitcnt vmcnt(2)
	ds_write_b128 v201, v[192:195] offset:49152
	s_waitcnt vmcnt(1)
	ds_write_b128 v201, v[196:199] offset:24576
	s_waitcnt vmcnt(0)
	ds_write_b128 v201, v[240:243] offset:57344
	global_load_dwordx4 v[236:239], v[134:135], off offset:640
	global_load_dwordx4 v[176:179], v[168:169], off offset:640
	global_load_dwordx4 v[180:183], v[170:171], off offset:640
	global_load_dwordx4 v[184:187], v[130:131], off offset:640
	global_load_dwordx4 v[188:191], v[142:143], off offset:640
	global_load_dwordx4 v[192:195], v[132:133], off offset:640
	global_load_dwordx4 v[196:199], v[146:147], off offset:640
	global_load_dwordx4 v[240:243], v[158:159], off offset:640
	v_mfma_f32_32x32x16_bf16 v[2:17], v[172:175], v[152:155], v[2:17]
	ds_read_b128 v[136:139], v223
	ds_read_b128 v[148:151], v222
	ds_read_b128 v[152:155], v222 offset:4096
	ds_read_b128 v[172:175], v223 offset:4096
	s_waitcnt lgkmcnt(2)
	v_mfma_f32_32x32x16_bf16 v[114:129], v[136:139], v[148:151], v[114:129]
	s_waitcnt lgkmcnt(1)
	v_mfma_f32_32x32x16_bf16 v[50:65], v[136:139], v[152:155], v[50:65]
	s_waitcnt lgkmcnt(0)
	v_mfma_f32_32x32x16_bf16 v[98:113], v[172:175], v[148:151], v[98:113]
	v_mfma_f32_32x32x16_bf16 v[34:49], v[172:175], v[152:155], v[34:49]
	ds_read_b128 v[136:139], v223 offset:8192
	ds_read_b128 v[172:175], v223 offset:12288
	s_waitcnt lgkmcnt(1)
	v_mfma_f32_32x32x16_bf16 v[82:97], v[136:139], v[148:151], v[82:97]
	v_mfma_f32_32x32x16_bf16 v[18:33], v[136:139], v[152:155], v[18:33]
	s_waitcnt lgkmcnt(0)
	v_mfma_f32_32x32x16_bf16 v[66:81], v[172:175], v[148:151], v[66:81]
	v_mfma_f32_32x32x16_bf16 v[2:17], v[172:175], v[152:155], v[2:17]
	ds_read_b128 v[136:139], v225
	ds_read_b128 v[148:151], v224
	ds_read_b128 v[152:155], v224 offset:4096
	ds_read_b128 v[172:175], v225 offset:4096
	s_waitcnt lgkmcnt(2)
	v_mfma_f32_32x32x16_bf16 v[114:129], v[136:139], v[148:151], v[114:129]
	s_waitcnt lgkmcnt(1)
	v_mfma_f32_32x32x16_bf16 v[50:65], v[136:139], v[152:155], v[50:65]
	s_waitcnt lgkmcnt(0)
	v_mfma_f32_32x32x16_bf16 v[98:113], v[172:175], v[148:151], v[98:113]
	v_mfma_f32_32x32x16_bf16 v[34:49], v[172:175], v[152:155], v[34:49]
	ds_read_b128 v[136:139], v225 offset:8192
	ds_read_b128 v[172:175], v225 offset:12288
	s_waitcnt lgkmcnt(1)
	v_mfma_f32_32x32x16_bf16 v[82:97], v[136:139], v[148:151], v[82:97]
	v_mfma_f32_32x32x16_bf16 v[18:33], v[136:139], v[152:155], v[18:33]
	s_waitcnt lgkmcnt(0)
	v_mfma_f32_32x32x16_bf16 v[66:81], v[172:175], v[148:151], v[66:81]
	v_mfma_f32_32x32x16_bf16 v[2:17], v[172:175], v[152:155], v[2:17]
	ds_read_b128 v[136:139], v227
	ds_read_b128 v[148:151], v226
	ds_read_b128 v[152:155], v226 offset:4096
	ds_read_b128 v[172:175], v227 offset:4096
	s_waitcnt lgkmcnt(2)
	v_mfma_f32_32x32x16_bf16 v[114:129], v[136:139], v[148:151], v[114:129]
	s_waitcnt lgkmcnt(1)
	v_mfma_f32_32x32x16_bf16 v[50:65], v[136:139], v[152:155], v[50:65]
	s_waitcnt lgkmcnt(0)
	v_mfma_f32_32x32x16_bf16 v[98:113], v[172:175], v[148:151], v[98:113]
	v_mfma_f32_32x32x16_bf16 v[34:49], v[172:175], v[152:155], v[34:49]
	ds_read_b128 v[136:139], v227 offset:8192
	ds_read_b128 v[172:175], v227 offset:12288
	s_waitcnt lgkmcnt(1)
	v_mfma_f32_32x32x16_bf16 v[82:97], v[136:139], v[148:151], v[82:97]
	v_mfma_f32_32x32x16_bf16 v[18:33], v[136:139], v[152:155], v[18:33]
	s_waitcnt lgkmcnt(0)
	v_mfma_f32_32x32x16_bf16 v[66:81], v[172:175], v[148:151], v[66:81]
	v_mfma_f32_32x32x16_bf16 v[2:17], v[172:175], v[152:155], v[2:17]
	ds_read_b128 v[136:139], v229
	ds_read_b128 v[148:151], v228
	ds_read_b128 v[152:155], v228 offset:4096
	ds_read_b128 v[172:175], v229 offset:4096
	s_waitcnt lgkmcnt(2)
	v_mfma_f32_32x32x16_bf16 v[114:129], v[136:139], v[148:151], v[114:129]
	s_waitcnt lgkmcnt(1)
	v_mfma_f32_32x32x16_bf16 v[50:65], v[136:139], v[152:155], v[50:65]
	s_waitcnt lgkmcnt(0)
	v_mfma_f32_32x32x16_bf16 v[98:113], v[172:175], v[148:151], v[98:113]
	v_mfma_f32_32x32x16_bf16 v[34:49], v[172:175], v[152:155], v[34:49]
	ds_read_b128 v[136:139], v229 offset:8192
	ds_read_b128 v[172:175], v229 offset:12288
	s_waitcnt lgkmcnt(1)
	v_mfma_f32_32x32x16_bf16 v[82:97], v[136:139], v[148:151], v[82:97]
	v_mfma_f32_32x32x16_bf16 v[18:33], v[136:139], v[152:155], v[18:33]
	s_waitcnt lgkmcnt(0)
	v_mfma_f32_32x32x16_bf16 v[66:81], v[172:175], v[148:151], v[66:81]
	s_barrier
; #define G_LOAD(AG, BG, kt, RA, RB) do { const int k0_ = (kt) * 64; int ac_ = k0_; if (g.remap) ac_ = k0_ < 512 ? k0_ : (k0_ < 1024 ? g.seg2 + k0_ - 512 : 2304 + k0_ - 1024); \
;     _Pragma("unroll") for (int i = 0; i < 4; ++i) { RA[i] = *(const u32x4*)(AG + (size_t)(64 * i) * g.lda + ac_); RB[i] = *(const u32x4*)(BG + (size_t)(64 * i) * g.K + k0_); } } while (0)
; #define G_WRITE(buf, RA, RB) do { _Pragma("unroll") for (int i = 0; i < 4; ++i) { *(u32x4*)(lds + (buf) * 65536 + i * 8192 + soff) = RA[i]; *(u32x4*)(lds + (buf) * 65536 + 32768 + i * 8192 + soff) = RB[i]; } } while (0)
; template <int EPI>
; DI void gemm_phase(char* lds, const Params& p, const GemmDesc g, int layer) {
;     ...
;     for (int kt = 0; kt < nk; kt += 2) {
;       const bool last = kt + 2 >= nk;
;       G_WRITE(1, ra0, rb0);
;       if (!last) G_LOAD(Ag, Bg, kt + 2, ra0, rb0); else if (has_next) G_LOAD(Agn, Bgn, 0, ra0, rb0);
;       G_COMPUTE(0);
;       __syncthreads();
;       if (!last || has_next) G_WRITE(0, ra0, rb0);
;       if (!last) G_LOAD(Ag, Bg, kt + 3, ra0, rb0); else if (has_next) G_LOAD(Agn, Bgn, 1, ra0, rb0);
;       G_COMPUTE(1);
;       __syncthreads();
	s_waitcnt vmcnt(6)
	ds_write_b128 v202, v[176:179]
	s_waitcnt vmcnt(5)
	ds_write_b128 v203, v[180:183]
	s_waitcnt vmcnt(4)
	ds_write_b128 v202, v[184:187] offset:8192
	s_waitcnt vmcnt(3)
	ds_write_b128 v203, v[188:191] offset:8192
	s_waitcnt vmcnt(2)
	ds_write_b128 v202, v[192:195] offset:16384
	s_waitcnt vmcnt(1)
	ds_write_b128 v203, v[196:199] offset:16384
	ds_write_b128 v202, v[236:239] offset:24576
	s_waitcnt vmcnt(0)
	ds_write_b128 v203, v[240:243] offset:24576
	global_load_dwordx4 v[236:239], v[168:169], off offset:768
	global_load_dwordx4 v[176:179], v[170:171], off offset:768
	global_load_dwordx4 v[180:183], v[130:131], off offset:768
	global_load_dwordx4 v[184:187], v[142:143], off offset:768
	global_load_dwordx4 v[188:191], v[132:133], off offset:768
	global_load_dwordx4 v[192:195], v[146:147], off offset:768
	global_load_dwordx4 v[196:199], v[134:135], off offset:768
	global_load_dwordx4 v[240:243], v[158:159], off offset:768
	v_mfma_f32_32x32x16_bf16 v[2:17], v[172:175], v[152:155], v[2:17]
	ds_read_b128 v[136:139], v205 offset:32768
	ds_read_b128 v[148:151], v204
	ds_read_b128 v[152:155], v204 offset:4096
	ds_read_b128 v[172:175], v205 offset:36864
	s_waitcnt lgkmcnt(2)
	v_mfma_f32_32x32x16_bf16 v[114:129], v[136:139], v[148:151], v[114:129]
	s_waitcnt lgkmcnt(1)
	v_mfma_f32_32x32x16_bf16 v[50:65], v[136:139], v[152:155], v[50:65]
	s_waitcnt lgkmcnt(0)
	v_mfma_f32_32x32x16_bf16 v[98:113], v[172:175], v[148:151], v[98:113]
	v_mfma_f32_32x32x16_bf16 v[34:49], v[172:175], v[152:155], v[34:49]
	ds_read_b128 v[136:139], v205 offset:40960
	ds_read_b128 v[172:175], v205 offset:45056
	s_waitcnt lgkmcnt(1)
	v_mfma_f32_32x32x16_bf16 v[82:97], v[136:139], v[148:151], v[82:97]
	v_mfma_f32_32x32x16_bf16 v[18:33], v[136:139], v[152:155], v[18:33]
	s_waitcnt lgkmcnt(0)
	v_mfma_f32_32x32x16_bf16 v[66:81], v[172:175], v[148:151], v[66:81]
	v_mfma_f32_32x32x16_bf16 v[2:17], v[172:175], v[152:155], v[2:17]
	ds_read_b128 v[136:139], v207 offset:32768
	ds_read_b128 v[148:151], v206
	ds_read_b128 v[152:155], v206 offset:4096
	ds_read_b128 v[172:175], v207 offset:36864
	s_waitcnt lgkmcnt(2)
	v_mfma_f32_32x32x16_bf16 v[114:129], v[136:139], v[148:151], v[114:129]
	s_waitcnt lgkmcnt(1)
	v_mfma_f32_32x32x16_bf16 v[50:65], v[136:139], v[152:155], v[50:65]
	s_waitcnt lgkmcnt(0)
	v_mfma_f32_32x32x16_bf16 v[98:113], v[172:175], v[148:151], v[98:113]
	v_mfma_f32_32x32x16_bf16 v[34:49], v[172:175], v[152:155], v[34:49]
	ds_read_b128 v[136:139], v207 offset:40960
	ds_read_b128 v[172:175], v207 offset:45056
	s_waitcnt lgkmcnt(1)
	v_mfma_f32_32x32x16_bf16 v[82:97], v[136:139], v[148:151], v[82:97]
	v_mfma_f32_32x32x16_bf16 v[18:33], v[136:139], v[152:155], v[18:33]
	s_waitcnt lgkmcnt(0)
	v_mfma_f32_32x32x16_bf16 v[66:81], v[172:175], v[148:151], v[66:81]
	v_mfma_f32_32x32x16_bf16 v[2:17], v[172:175], v[152:155], v[2:17]
	ds_read_b128 v[136:139], v209 offset:32768
	ds_read_b128 v[148:151], v208
	ds_read_b128 v[152:155], v208 offset:4096
	ds_read_b128 v[172:175], v209 offset:36864
	s_waitcnt lgkmcnt(2)
	v_mfma_f32_32x32x16_bf16 v[114:129], v[136:139], v[148:151], v[114:129]
	s_waitcnt lgkmcnt(1)
	v_mfma_f32_32x32x16_bf16 v[50:65], v[136:139], v[152:155], v[50:65]
	s_waitcnt lgkmcnt(0)
	v_mfma_f32_32x32x16_bf16 v[98:113], v[172:175], v[148:151], v[98:113]
	v_mfma_f32_32x32x16_bf16 v[34:49], v[172:175], v[152:155], v[34:49]
	ds_read_b128 v[136:139], v209 offset:40960
	ds_read_b128 v[172:175], v209 offset:45056
	s_waitcnt lgkmcnt(1)
	v_mfma_f32_32x32x16_bf16 v[82:97], v[136:139], v[148:151], v[82:97]
	v_mfma_f32_32x32x16_bf16 v[18:33], v[136:139], v[152:155], v[18:33]
	s_waitcnt lgkmcnt(0)
	v_mfma_f32_32x32x16_bf16 v[66:81], v[172:175], v[148:151], v[66:81]
	v_mfma_f32_32x32x16_bf16 v[2:17], v[172:175], v[152:155], v[2:17]
	ds_read_b128 v[136:139], v211 offset:32768
	ds_read_b128 v[148:151], v210
	ds_read_b128 v[152:155], v210 offset:4096
	ds_read_b128 v[172:175], v211 offset:36864
	s_waitcnt lgkmcnt(2)
	v_mfma_f32_32x32x16_bf16 v[114:129], v[136:139], v[148:151], v[114:129]
	s_waitcnt lgkmcnt(1)
	v_mfma_f32_32x32x16_bf16 v[50:65], v[136:139], v[152:155], v[50:65]
	s_waitcnt lgkmcnt(0)
	v_mfma_f32_32x32x16_bf16 v[98:113], v[172:175], v[148:151], v[98:113]
	v_mfma_f32_32x32x16_bf16 v[34:49], v[172:175], v[152:155], v[34:49]
	ds_read_b128 v[136:139], v211 offset:40960
	ds_read_b128 v[172:175], v211 offset:45056
	s_waitcnt lgkmcnt(1)
	v_mfma_f32_32x32x16_bf16 v[82:97], v[136:139], v[148:151], v[82:97]
	v_mfma_f32_32x32x16_bf16 v[18:33], v[136:139], v[152:155], v[18:33]
	s_waitcnt lgkmcnt(0)
	v_mfma_f32_32x32x16_bf16 v[66:81], v[172:175], v[148:151], v[66:81]
	s_barrier
; #define G_LOAD(AG, BG, kt, RA, RB) do { const int k0_ = (kt) * 64; int ac_ = k0_; if (g.remap) ac_ = k0_ < 512 ? k0_ : (k0_ < 1024 ? g.seg2 + k0_ - 512 : 2304 + k0_ - 1024); \
;     _Pragma("unroll") for (int i = 0; i < 4; ++i) { RA[i] = *(const u32x4*)(AG + (size_t)(64 * i) * g.lda + ac_); RB[i] = *(const u32x4*)(BG + (size_t)(64 * i) * g.K + k0_); } } while (0)
; #define G_WRITE(buf, RA, RB) do { _Pragma("unroll") for (int i = 0; i < 4; ++i) { *(u32x4*)(lds + (buf) * 65536 + i * 8192 + soff) = RA[i]; *(u32x4*)(lds + (buf) * 65536 + 32768 + i * 8192 + soff) = RB[i]; } } while (0)
; template <int EPI>
; DI void gemm_phase(char* lds, const Params& p, const GemmDesc g, int layer) {
;     ...
;     for (int kt = 0; kt < nk; kt += 2) {
;       const bool last = kt + 2 >= nk;
;       G_WRITE(1, ra0, rb0);
;       if (!last) G_LOAD(Ag, Bg, kt + 2, ra0, rb0); else if (has_next) G_LOAD(Agn, Bgn, 0, ra0, rb0);
;       G_COMPUTE(0);
;       __syncthreads();
;       if (!last || has_next) G_WRITE(0, ra0, rb0);
;       if (!last) G_LOAD(Ag, Bg, kt + 3, ra0, rb0); else if (has_next) G_LOAD(Agn, Bgn, 1, ra0, rb0);
;       G_COMPUTE(1);
;       __syncthreads();
	s_waitcnt vmcnt(7)
	ds_write_b128 v201, v[236:239]
	s_waitcnt vmcnt(6)
	ds_write_b128 v201, v[176:179] offset:32768
	s_waitcnt vmcnt(5)
	ds_write_b128 v201, v[180:183] offset:8192
	s_waitcnt vmcnt(4)
	ds_write_b128 v201, v[184:187] offset:40960
	s_waitcnt vmcnt(3)
	ds_write_b128 v201, v[188:191] offset:16384
	s_waitcnt vmcnt(2)
	ds_write_b128 v201, v[192:195] offset:49152
	s_waitcnt vmcnt(1)
	ds_write_b128 v201, v[196:199] offset:24576
	s_waitcnt vmcnt(0)
	ds_write_b128 v201, v[240:243] offset:57344
	global_load_dwordx4 v[236:239], v[134:135], off offset:896
	global_load_dwordx4 v[240:243], v[168:169], off offset:896
	global_load_dwordx4 v[176:179], v[170:171], off offset:896
	global_load_dwordx4 v[180:183], v[130:131], off offset:896
	global_load_dwordx4 v[184:187], v[142:143], off offset:896
	global_load_dwordx4 v[130:133], v[132:133], off offset:896
	global_load_dwordx4 v[188:191], v[146:147], off offset:896
	global_load_dwordx4 v[244:247], v[158:159], off offset:896
	v_mfma_f32_32x32x16_bf16 v[2:17], v[172:175], v[152:155], v[2:17]
	ds_read_b128 v[136:139], v223
	ds_read_b128 v[148:151], v222
	ds_read_b128 v[152:155], v222 offset:4096
	ds_read_b128 v[172:175], v223 offset:4096
	s_waitcnt lgkmcnt(2)
	v_mfma_f32_32x32x16_bf16 v[114:129], v[136:139], v[148:151], v[114:129]
	s_waitcnt lgkmcnt(1)
	v_mfma_f32_32x32x16_bf16 v[50:65], v[136:139], v[152:155], v[50:65]
	s_waitcnt lgkmcnt(0)
	v_mfma_f32_32x32x16_bf16 v[98:113], v[172:175], v[148:151], v[98:113]
	v_mfma_f32_32x32x16_bf16 v[34:49], v[172:175], v[152:155], v[34:49]
	ds_read_b128 v[136:139], v223 offset:8192
	ds_read_b128 v[172:175], v223 offset:12288
	s_waitcnt lgkmcnt(1)
	v_mfma_f32_32x32x16_bf16 v[82:97], v[136:139], v[148:151], v[82:97]
	v_mfma_f32_32x32x16_bf16 v[18:33], v[136:139], v[152:155], v[18:33]
	s_waitcnt lgkmcnt(0)
	v_mfma_f32_32x32x16_bf16 v[66:81], v[172:175], v[148:151], v[66:81]
	v_mfma_f32_32x32x16_bf16 v[2:17], v[172:175], v[152:155], v[2:17]
	ds_read_b128 v[136:139], v225
	ds_read_b128 v[148:151], v224
	ds_read_b128 v[152:155], v224 offset:4096
	ds_read_b128 v[172:175], v225 offset:4096
	s_waitcnt lgkmcnt(2)
	v_mfma_f32_32x32x16_bf16 v[114:129], v[136:139], v[148:151], v[114:129]
	s_waitcnt lgkmcnt(1)
	v_mfma_f32_32x32x16_bf16 v[50:65], v[136:139], v[152:155], v[50:65]
	s_waitcnt lgkmcnt(0)
	v_mfma_f32_32x32x16_bf16 v[98:113], v[172:175], v[148:151], v[98:113]
	v_mfma_f32_32x32x16_bf16 v[34:49], v[172:175], v[152:155], v[34:49]
	ds_read_b128 v[136:139], v225 offset:8192
	ds_read_b128 v[172:175], v225 offset:12288
	s_waitcnt lgkmcnt(1)
	v_mfma_f32_32x32x16_bf16 v[82:97], v[136:139], v[148:151], v[82:97]
	v_mfma_f32_32x32x16_bf16 v[18:33], v[136:139], v[152:155], v[18:33]
	s_waitcnt lgkmcnt(0)
	v_mfma_f32_32x32x16_bf16 v[66:81], v[172:175], v[148:151], v[66:81]
	v_mfma_f32_32x32x16_bf16 v[2:17], v[172:175], v[152:155], v[2:17]
	ds_read_b128 v[136:139], v227
	ds_read_b128 v[148:151], v226
	ds_read_b128 v[152:155], v226 offset:4096
	ds_read_b128 v[172:175], v227 offset:4096
	s_waitcnt lgkmcnt(2)
	v_mfma_f32_32x32x16_bf16 v[114:129], v[136:139], v[148:151], v[114:129]
	s_waitcnt lgkmcnt(1)
	v_mfma_f32_32x32x16_bf16 v[50:65], v[136:139], v[152:155], v[50:65]
	s_waitcnt lgkmcnt(0)
	v_mfma_f32_32x32x16_bf16 v[98:113], v[172:175], v[148:151], v[98:113]
	v_mfma_f32_32x32x16_bf16 v[34:49], v[172:175], v[152:155], v[34:49]
	ds_read_b128 v[136:139], v227 offset:8192
	ds_read_b128 v[172:175], v227 offset:12288
	s_waitcnt lgkmcnt(1)
	v_mfma_f32_32x32x16_bf16 v[82:97], v[136:139], v[148:151], v[82:97]
	v_mfma_f32_32x32x16_bf16 v[18:33], v[136:139], v[152:155], v[18:33]
	s_waitcnt lgkmcnt(0)
	v_mfma_f32_32x32x16_bf16 v[66:81], v[172:175], v[148:151], v[66:81]
	v_mfma_f32_32x32x16_bf16 v[2:17], v[172:175], v[152:155], v[2:17]
	ds_read_b128 v[136:139], v229
	ds_read_b128 v[148:151], v228
	ds_read_b128 v[152:155], v228 offset:4096
	ds_read_b128 v[172:175], v229 offset:4096
	s_waitcnt lgkmcnt(2)
	v_mfma_f32_32x32x16_bf16 v[114:129], v[136:139], v[148:151], v[114:129]
	s_waitcnt lgkmcnt(1)
	v_mfma_f32_32x32x16_bf16 v[50:65], v[136:139], v[152:155], v[50:65]
	s_waitcnt lgkmcnt(0)
	v_mfma_f32_32x32x16_bf16 v[98:113], v[172:175], v[148:151], v[98:113]
	v_mfma_f32_32x32x16_bf16 v[34:49], v[172:175], v[152:155], v[34:49]
	ds_read_b128 v[136:139], v229 offset:8192
	ds_read_b128 v[172:175], v229 offset:12288
	s_waitcnt lgkmcnt(1)
	v_mfma_f32_32x32x16_bf16 v[82:97], v[136:139], v[148:151], v[82:97]
	v_mfma_f32_32x32x16_bf16 v[18:33], v[136:139], v[152:155], v[18:33]
	s_nop 0
	s_nop 0
	s_nop 0
	s_waitcnt lgkmcnt(0)
	v_mfma_f32_32x32x16_bf16 v[66:81], v[172:175], v[148:151], v[66:81]
	s_barrier
; #define G_LOAD(AG, BG, kt, RA, RB) do { const int k0_ = (kt) * 64; int ac_ = k0_; if (g.remap) ac_ = k0_ < 512 ? k0_ : (k0_ < 1024 ? g.seg2 + k0_ - 512 : 2304 + k0_ - 1024); \
;     _Pragma("unroll") for (int i = 0; i < 4; ++i) { RA[i] = *(const u32x4*)(AG + (size_t)(64 * i) * g.lda + ac_); RB[i] = *(const u32x4*)(BG + (size_t)(64 * i) * g.K + k0_); } } while (0)
; #define G_WRITE(buf, RA, RB) do { _Pragma("unroll") for (int i = 0; i < 4; ++i) { *(u32x4*)(lds + (buf) * 65536 + i * 8192 + soff) = RA[i]; *(u32x4*)(lds + (buf) * 65536 + 32768 + i * 8192 + soff) = RB[i]; } } while (0)
; template <int EPI>
; DI void gemm_phase(char* lds, const Params& p, const GemmDesc g, int layer) {
;     ...
;     for (int kt = 0; kt < nk; kt += 2) {
;       const bool last = kt + 2 >= nk;
;       G_WRITE(1, ra0, rb0);
;       if (!last) G_LOAD(Ag, Bg, kt + 2, ra0, rb0); else if (has_next) G_LOAD(Agn, Bgn, 0, ra0, rb0);
;       G_COMPUTE(0);
;       __syncthreads();
;       if (!last || has_next) G_WRITE(0, ra0, rb0);
;       if (!last) G_LOAD(Ag, Bg, kt + 3, ra0, rb0); else if (has_next) G_LOAD(Agn, Bgn, 1, ra0, rb0);
;       G_COMPUTE(1);
;       __syncthreads();
	s_waitcnt vmcnt(6)
	ds_write_b128 v202, v[240:243]
	s_waitcnt vmcnt(5)
	ds_write_b128 v203, v[176:179]
	s_waitcnt vmcnt(4)
	ds_write_b128 v202, v[180:183] offset:8192
	s_waitcnt vmcnt(3)
	ds_write_b128 v203, v[184:187] offset:8192
	s_waitcnt vmcnt(2)
	ds_write_b128 v202, v[130:133] offset:16384
	s_waitcnt vmcnt(1)
	ds_write_b128 v203, v[188:191] offset:16384
	ds_write_b128 v202, v[236:239] offset:24576
	s_waitcnt vmcnt(0)
	ds_write_b128 v203, v[244:247] offset:24576
	ds_read_b128 v[130:133], v205 offset:32768
	ds_read_b128 v[134:137], v204
	ds_read_b128 v[138:141], v204 offset:4096
	ds_read_b128 v[148:151], v205 offset:36864
	v_mfma_f32_32x32x16_bf16 v[2:17], v[172:175], v[152:155], v[2:17]
	s_waitcnt lgkmcnt(2)
	v_mfma_f32_32x32x16_bf16 v[114:129], v[130:133], v[134:137], v[114:129]
	s_waitcnt lgkmcnt(1)
	v_mfma_f32_32x32x16_bf16 v[50:65], v[130:133], v[138:141], v[50:65]
	s_waitcnt lgkmcnt(0)
	v_mfma_f32_32x32x16_bf16 v[98:113], v[148:151], v[134:137], v[98:113]
	v_mfma_f32_32x32x16_bf16 v[34:49], v[148:151], v[138:141], v[34:49]
	ds_read_b128 v[130:133], v205 offset:40960
	ds_read_b128 v[148:151], v205 offset:45056
	s_waitcnt lgkmcnt(1)
	v_mfma_f32_32x32x16_bf16 v[82:97], v[130:133], v[134:137], v[82:97]
	v_mfma_f32_32x32x16_bf16 v[18:33], v[130:133], v[138:141], v[18:33]
	s_waitcnt lgkmcnt(0)
	v_mfma_f32_32x32x16_bf16 v[66:81], v[148:151], v[134:137], v[66:81]
	v_mfma_f32_32x32x16_bf16 v[2:17], v[148:151], v[138:141], v[2:17]
	ds_read_b128 v[130:133], v207 offset:32768
	ds_read_b128 v[134:137], v206
	ds_read_b128 v[138:141], v206 offset:4096
	ds_read_b128 v[148:151], v207 offset:36864
	s_waitcnt lgkmcnt(2)
	v_mfma_f32_32x32x16_bf16 v[114:129], v[130:133], v[134:137], v[114:129]
	s_waitcnt lgkmcnt(1)
	v_mfma_f32_32x32x16_bf16 v[50:65], v[130:133], v[138:141], v[50:65]
	s_waitcnt lgkmcnt(0)
	v_mfma_f32_32x32x16_bf16 v[98:113], v[148:151], v[134:137], v[98:113]
	v_mfma_f32_32x32x16_bf16 v[34:49], v[148:151], v[138:141], v[34:49]
	ds_read_b128 v[130:133], v207 offset:40960
	ds_read_b128 v[148:151], v207 offset:45056
	s_waitcnt lgkmcnt(1)
	v_mfma_f32_32x32x16_bf16 v[82:97], v[130:133], v[134:137], v[82:97]
	v_mfma_f32_32x32x16_bf16 v[18:33], v[130:133], v[138:141], v[18:33]
	s_waitcnt lgkmcnt(0)
	v_mfma_f32_32x32x16_bf16 v[66:81], v[148:151], v[134:137], v[66:81]
	v_mfma_f32_32x32x16_bf16 v[2:17], v[148:151], v[138:141], v[2:17]
	ds_read_b128 v[130:133], v209 offset:32768
	ds_read_b128 v[134:137], v208
	ds_read_b128 v[138:141], v208 offset:4096
	ds_read_b128 v[148:151], v209 offset:36864
	s_waitcnt lgkmcnt(2)
	v_mfma_f32_32x32x16_bf16 v[114:129], v[130:133], v[134:137], v[114:129]
	s_waitcnt lgkmcnt(1)
	v_mfma_f32_32x32x16_bf16 v[50:65], v[130:133], v[138:141], v[50:65]
	s_waitcnt lgkmcnt(0)
	v_mfma_f32_32x32x16_bf16 v[98:113], v[148:151], v[134:137], v[98:113]
	v_mfma_f32_32x32x16_bf16 v[34:49], v[148:151], v[138:141], v[34:49]
	ds_read_b128 v[130:133], v209 offset:40960
	ds_read_b128 v[148:151], v209 offset:45056
	s_waitcnt lgkmcnt(1)
	v_mfma_f32_32x32x16_bf16 v[82:97], v[130:133], v[134:137], v[82:97]
	v_mfma_f32_32x32x16_bf16 v[18:33], v[130:133], v[138:141], v[18:33]
	s_waitcnt lgkmcnt(0)
	v_mfma_f32_32x32x16_bf16 v[66:81], v[148:151], v[134:137], v[66:81]
	v_mfma_f32_32x32x16_bf16 v[2:17], v[148:151], v[138:141], v[2:17]
	ds_read_b128 v[130:133], v211 offset:32768
	ds_read_b128 v[138:141], v210
	ds_read_b128 v[148:151], v210 offset:4096
	ds_read_b128 v[134:137], v211 offset:36864
	ds_read_b128 v[152:155], v211 offset:40960
	ds_read_b128 v[176:179], v211 offset:45056
	global_load_dwordx4 v[172:175], v[170:171], off offset:1024
	s_waitcnt lgkmcnt(4)
	v_mfma_f32_32x32x16_bf16 v[114:129], v[130:133], v[138:141], v[114:129]
	s_waitcnt lgkmcnt(3)
	v_mfma_f32_32x32x16_bf16 v[50:65], v[130:133], v[148:151], v[50:65]
	v_lshl_add_u64 v[130:131], v[168:169], 0, s[14:15]
	v_add_co_u32_e32 v132, vcc, s34, v130
	s_nop 1
	v_addc_co_u32_e32 v133, vcc, 0, v131, vcc
	global_load_dwordx4 v[180:183], v[130:131], off offset:1024
	global_load_dwordx4 v[184:187], v[132:133], off offset:1024
	s_waitcnt lgkmcnt(2)
	v_mfma_f32_32x32x16_bf16 v[98:113], v[134:137], v[138:141], v[98:113]
	v_mfma_f32_32x32x16_bf16 v[34:49], v[134:137], v[148:151], v[34:49]
	v_add_co_u32_e32 v134, vcc, s0, v130
	s_mov_b32 s0, 0x79000
	s_nop 0
	v_addc_co_u32_e32 v135, vcc, 0, v131, vcc
	v_add_co_u32_e32 v136, vcc, s1, v130
	s_waitcnt lgkmcnt(1)
	v_mfma_f32_32x32x16_bf16 v[82:97], v[152:155], v[138:141], v[82:97]
	v_addc_co_u32_e32 v137, vcc, 0, v131, vcc
	v_mfma_f32_32x32x16_bf16 v[18:33], v[152:155], v[148:151], v[18:33]
	global_load_dwordx4 v[152:155], v[142:143], off offset:1024
	global_load_dwordx4 v[188:191], v[146:147], off offset:1024
	global_load_dwordx4 v[192:195], v[134:135], off offset:1024
	global_load_dwordx4 v[196:199], v[136:137], off offset:1024
	s_waitcnt lgkmcnt(0)
	v_mfma_f32_32x32x16_bf16 v[66:81], v[176:179], v[138:141], v[66:81]
	global_load_dwordx4 v[138:141], v[158:159], off offset:1024
	s_barrier
; #define G_LOAD(AG, BG, kt, RA, RB) do { const int k0_ = (kt) * 64; int ac_ = k0_; if (g.remap) ac_ = k0_ < 512 ? k0_ : (k0_ < 1024 ? g.seg2 + k0_ - 512 : 2304 + k0_ - 1024); \
;     _Pragma("unroll") for (int i = 0; i < 4; ++i) { RA[i] = *(const u32x4*)(AG + (size_t)(64 * i) * g.lda + ac_); RB[i] = *(const u32x4*)(BG + (size_t)(64 * i) * g.K + k0_); } } while (0)
; #define G_WRITE(buf, RA, RB) do { _Pragma("unroll") for (int i = 0; i < 4; ++i) { *(u32x4*)(lds + (buf) * 65536 + i * 8192 + soff) = RA[i]; *(u32x4*)(lds + (buf) * 65536 + 32768 + i * 8192 + soff) = RB[i]; } } while (0)
; template <int EPI>
; DI void gemm_phase(char* lds, const Params& p, const GemmDesc g, int layer) {
;     ...
;     for (int kt = 0; kt < nk; kt += 2) {
;       const bool last = kt + 2 >= nk;
;       G_WRITE(1, ra0, rb0);
;       if (!last) G_LOAD(Ag, Bg, kt + 2, ra0, rb0); else if (has_next) G_LOAD(Agn, Bgn, 0, ra0, rb0);
;       G_COMPUTE(0);
;       __syncthreads();
;       if (!last || has_next) G_WRITE(0, ra0, rb0);
;       if (!last) G_LOAD(Ag, Bg, kt + 3, ra0, rb0); else if (has_next) G_LOAD(Agn, Bgn, 1, ra0, rb0);
;       G_COMPUTE(1);
;       __syncthreads();
	s_waitcnt vmcnt(6)
	ds_write_b128 v201, v[180:183]
	ds_write_b128 v201, v[172:175] offset:32768
	s_waitcnt vmcnt(5)
	ds_write_b128 v201, v[184:187] offset:8192
	s_waitcnt vmcnt(4)
	ds_write_b128 v201, v[152:155] offset:40960
	s_waitcnt vmcnt(2)
	ds_write_b128 v201, v[192:195] offset:16384
	ds_write_b128 v201, v[188:191] offset:49152
	s_waitcnt vmcnt(1)
	ds_write_b128 v201, v[196:199] offset:24576
	s_waitcnt vmcnt(0)
	ds_write_b128 v201, v[138:141] offset:57344
	global_load_dwordx4 v[236:239], v[132:133], off offset:1152
	global_load_dwordx4 v[240:243], v[130:131], off offset:1152
	global_load_dwordx4 v[180:183], v[170:171], off offset:1152
	global_load_dwordx4 v[184:187], v[142:143], off offset:1152
	global_load_dwordx4 v[188:191], v[136:137], off offset:1152
	global_load_dwordx4 v[192:195], v[134:135], off offset:1152
	global_load_dwordx4 v[196:199], v[146:147], off offset:1152
	global_load_dwordx4 v[244:247], v[158:159], off offset:1152
	v_mfma_f32_32x32x16_bf16 v[2:17], v[176:179], v[148:151], v[2:17]
	ds_read_b128 v[138:141], v223
	ds_read_b128 v[148:151], v222
	ds_read_b128 v[152:155], v222 offset:4096
	ds_read_b128 v[172:175], v223 offset:4096
	s_waitcnt lgkmcnt(2)
	v_mfma_f32_32x32x16_bf16 v[114:129], v[138:141], v[148:151], v[114:129]
	s_waitcnt lgkmcnt(1)
	v_mfma_f32_32x32x16_bf16 v[50:65], v[138:141], v[152:155], v[50:65]
	s_waitcnt lgkmcnt(0)
	v_mfma_f32_32x32x16_bf16 v[98:113], v[172:175], v[148:151], v[98:113]
	v_mfma_f32_32x32x16_bf16 v[34:49], v[172:175], v[152:155], v[34:49]
	ds_read_b128 v[138:141], v223 offset:8192
	ds_read_b128 v[172:175], v223 offset:12288
	s_waitcnt lgkmcnt(1)
	v_mfma_f32_32x32x16_bf16 v[82:97], v[138:141], v[148:151], v[82:97]
	v_mfma_f32_32x32x16_bf16 v[18:33], v[138:141], v[152:155], v[18:33]
	s_waitcnt lgkmcnt(0)
	v_mfma_f32_32x32x16_bf16 v[66:81], v[172:175], v[148:151], v[66:81]
	v_mfma_f32_32x32x16_bf16 v[2:17], v[172:175], v[152:155], v[2:17]
	ds_read_b128 v[138:141], v225
	ds_read_b128 v[148:151], v224
	ds_read_b128 v[152:155], v224 offset:4096
	ds_read_b128 v[172:175], v225 offset:4096
	s_waitcnt lgkmcnt(2)
	v_mfma_f32_32x32x16_bf16 v[114:129], v[138:141], v[148:151], v[114:129]
	s_waitcnt lgkmcnt(1)
	v_mfma_f32_32x32x16_bf16 v[50:65], v[138:141], v[152:155], v[50:65]
	s_waitcnt lgkmcnt(0)
	v_mfma_f32_32x32x16_bf16 v[98:113], v[172:175], v[148:151], v[98:113]
	v_mfma_f32_32x32x16_bf16 v[34:49], v[172:175], v[152:155], v[34:49]
	ds_read_b128 v[138:141], v225 offset:8192
	ds_read_b128 v[172:175], v225 offset:12288
	s_waitcnt lgkmcnt(1)
	v_mfma_f32_32x32x16_bf16 v[82:97], v[138:141], v[148:151], v[82:97]
	v_mfma_f32_32x32x16_bf16 v[18:33], v[138:141], v[152:155], v[18:33]
	s_waitcnt lgkmcnt(0)
	v_mfma_f32_32x32x16_bf16 v[66:81], v[172:175], v[148:151], v[66:81]
	v_mfma_f32_32x32x16_bf16 v[2:17], v[172:175], v[152:155], v[2:17]
	ds_read_b128 v[138:141], v227
	ds_read_b128 v[148:151], v226
	ds_read_b128 v[152:155], v226 offset:4096
	ds_read_b128 v[172:175], v227 offset:4096
	s_waitcnt lgkmcnt(2)
	v_mfma_f32_32x32x16_bf16 v[114:129], v[138:141], v[148:151], v[114:129]
	s_waitcnt lgkmcnt(1)
	v_mfma_f32_32x32x16_bf16 v[50:65], v[138:141], v[152:155], v[50:65]
	s_waitcnt lgkmcnt(0)
	v_mfma_f32_32x32x16_bf16 v[98:113], v[172:175], v[148:151], v[98:113]
	v_mfma_f32_32x32x16_bf16 v[34:49], v[172:175], v[152:155], v[34:49]
	ds_read_b128 v[138:141], v227 offset:8192
	ds_read_b128 v[172:175], v227 offset:12288
	s_waitcnt lgkmcnt(1)
	v_mfma_f32_32x32x16_bf16 v[82:97], v[138:141], v[148:151], v[82:97]
	v_mfma_f32_32x32x16_bf16 v[18:33], v[138:141], v[152:155], v[18:33]
	s_waitcnt lgkmcnt(0)
	v_mfma_f32_32x32x16_bf16 v[66:81], v[172:175], v[148:151], v[66:81]
	v_mfma_f32_32x32x16_bf16 v[2:17], v[172:175], v[152:155], v[2:17]
	ds_read_b128 v[138:141], v229
	ds_read_b128 v[148:151], v228
	ds_read_b128 v[152:155], v228 offset:4096
	ds_read_b128 v[172:175], v229 offset:4096
	s_waitcnt lgkmcnt(2)
	v_mfma_f32_32x32x16_bf16 v[114:129], v[138:141], v[148:151], v[114:129]
	s_waitcnt lgkmcnt(1)
	v_mfma_f32_32x32x16_bf16 v[50:65], v[138:141], v[152:155], v[50:65]
	s_waitcnt lgkmcnt(0)
	v_mfma_f32_32x32x16_bf16 v[98:113], v[172:175], v[148:151], v[98:113]
	v_mfma_f32_32x32x16_bf16 v[34:49], v[172:175], v[152:155], v[34:49]
	ds_read_b128 v[138:141], v229 offset:8192
	ds_read_b128 v[172:175], v229 offset:12288
	s_waitcnt lgkmcnt(1)
	v_mfma_f32_32x32x16_bf16 v[82:97], v[138:141], v[148:151], v[82:97]
	v_mfma_f32_32x32x16_bf16 v[18:33], v[138:141], v[152:155], v[18:33]
	s_waitcnt lgkmcnt(0)
	v_mfma_f32_32x32x16_bf16 v[66:81], v[172:175], v[148:151], v[66:81]
	s_barrier
; #define G_LOAD(AG, BG, kt, RA, RB) do { const int k0_ = (kt) * 64; int ac_ = k0_; if (g.remap) ac_ = k0_ < 512 ? k0_ : (k0_ < 1024 ? g.seg2 + k0_ - 512 : 2304 + k0_ - 1024); \
;     _Pragma("unroll") for (int i = 0; i < 4; ++i) { RA[i] = *(const u32x4*)(AG + (size_t)(64 * i) * g.lda + ac_); RB[i] = *(const u32x4*)(BG + (size_t)(64 * i) * g.K + k0_); } } while (0)
; #define G_WRITE(buf, RA, RB) do { _Pragma("unroll") for (int i = 0; i < 4; ++i) { *(u32x4*)(lds + (buf) * 65536 + i * 8192 + soff) = RA[i]; *(u32x4*)(lds + (buf) * 65536 + 32768 + i * 8192 + soff) = RB[i]; } } while (0)
; template <int EPI>
; DI void gemm_phase(char* lds, const Params& p, const GemmDesc g, int layer) {
;     ...
;     for (int kt = 0; kt < nk; kt += 2) {
;       const bool last = kt + 2 >= nk;
;       G_WRITE(1, ra0, rb0);
;       if (!last) G_LOAD(Ag, Bg, kt + 2, ra0, rb0); else if (has_next) G_LOAD(Agn, Bgn, 0, ra0, rb0);
;       G_COMPUTE(0);
;       __syncthreads();
;       if (!last || has_next) G_WRITE(0, ra0, rb0);
;       if (!last) G_LOAD(Ag, Bg, kt + 3, ra0, rb0); else if (has_next) G_LOAD(Agn, Bgn, 1, ra0, rb0);
;       G_COMPUTE(1);
;       __syncthreads();
	s_waitcnt vmcnt(6)
	ds_write_b128 v202, v[240:243]
	s_waitcnt vmcnt(5)
	ds_write_b128 v203, v[180:183]
	ds_write_b128 v202, v[236:239] offset:8192
	s_waitcnt vmcnt(4)
	ds_write_b128 v203, v[184:187] offset:8192
	s_waitcnt vmcnt(2)
	ds_write_b128 v202, v[192:195] offset:16384
	s_waitcnt vmcnt(1)
	ds_write_b128 v203, v[196:199] offset:16384
	ds_write_b128 v202, v[188:191] offset:24576
	s_waitcnt vmcnt(0)
	ds_write_b128 v203, v[244:247] offset:24576
	global_load_dwordx4 v[236:239], v[170:171], off offset:1280
	global_load_dwordx4 v[176:179], v[130:131], off offset:1280
	global_load_dwordx4 v[180:183], v[132:133], off offset:1280
	global_load_dwordx4 v[184:187], v[142:143], off offset:1280
	global_load_dwordx4 v[188:191], v[146:147], off offset:1280
	global_load_dwordx4 v[192:195], v[134:135], off offset:1280
	global_load_dwordx4 v[196:199], v[136:137], off offset:1280
	global_load_dwordx4 v[240:243], v[158:159], off offset:1280
	v_mfma_f32_32x32x16_bf16 v[2:17], v[172:175], v[152:155], v[2:17]
	ds_read_b128 v[138:141], v205 offset:32768
	ds_read_b128 v[148:151], v204
	ds_read_b128 v[152:155], v204 offset:4096
	ds_read_b128 v[172:175], v205 offset:36864
	s_waitcnt lgkmcnt(2)
	v_mfma_f32_32x32x16_bf16 v[114:129], v[138:141], v[148:151], v[114:129]
	s_waitcnt lgkmcnt(1)
	v_mfma_f32_32x32x16_bf16 v[50:65], v[138:141], v[152:155], v[50:65]
	s_waitcnt lgkmcnt(0)
	v_mfma_f32_32x32x16_bf16 v[98:113], v[172:175], v[148:151], v[98:113]
	v_mfma_f32_32x32x16_bf16 v[34:49], v[172:175], v[152:155], v[34:49]
	ds_read_b128 v[138:141], v205 offset:40960
	ds_read_b128 v[172:175], v205 offset:45056
	s_waitcnt lgkmcnt(1)
	v_mfma_f32_32x32x16_bf16 v[82:97], v[138:141], v[148:151], v[82:97]
	v_mfma_f32_32x32x16_bf16 v[18:33], v[138:141], v[152:155], v[18:33]
	s_waitcnt lgkmcnt(0)
	v_mfma_f32_32x32x16_bf16 v[66:81], v[172:175], v[148:151], v[66:81]
	v_mfma_f32_32x32x16_bf16 v[2:17], v[172:175], v[152:155], v[2:17]
	ds_read_b128 v[138:141], v207 offset:32768
	ds_read_b128 v[148:151], v206
	ds_read_b128 v[152:155], v206 offset:4096
	ds_read_b128 v[172:175], v207 offset:36864
	s_waitcnt lgkmcnt(2)
	v_mfma_f32_32x32x16_bf16 v[114:129], v[138:141], v[148:151], v[114:129]
	s_waitcnt lgkmcnt(1)
	v_mfma_f32_32x32x16_bf16 v[50:65], v[138:141], v[152:155], v[50:65]
	s_waitcnt lgkmcnt(0)
	v_mfma_f32_32x32x16_bf16 v[98:113], v[172:175], v[148:151], v[98:113]
	v_mfma_f32_32x32x16_bf16 v[34:49], v[172:175], v[152:155], v[34:49]
	ds_read_b128 v[138:141], v207 offset:40960
	ds_read_b128 v[172:175], v207 offset:45056
	s_waitcnt lgkmcnt(1)
	v_mfma_f32_32x32x16_bf16 v[82:97], v[138:141], v[148:151], v[82:97]
	v_mfma_f32_32x32x16_bf16 v[18:33], v[138:141], v[152:155], v[18:33]
	s_waitcnt lgkmcnt(0)
	v_mfma_f32_32x32x16_bf16 v[66:81], v[172:175], v[148:151], v[66:81]
	v_mfma_f32_32x32x16_bf16 v[2:17], v[172:175], v[152:155], v[2:17]
	ds_read_b128 v[138:141], v209 offset:32768
	ds_read_b128 v[148:151], v208
	ds_read_b128 v[152:155], v208 offset:4096
	ds_read_b128 v[172:175], v209 offset:36864
	s_waitcnt lgkmcnt(2)
	v_mfma_f32_32x32x16_bf16 v[114:129], v[138:141], v[148:151], v[114:129]
	s_waitcnt lgkmcnt(1)
	v_mfma_f32_32x32x16_bf16 v[50:65], v[138:141], v[152:155], v[50:65]
	s_waitcnt lgkmcnt(0)
	v_mfma_f32_32x32x16_bf16 v[98:113], v[172:175], v[148:151], v[98:113]
	v_mfma_f32_32x32x16_bf16 v[34:49], v[172:175], v[152:155], v[34:49]
	ds_read_b128 v[138:141], v209 offset:40960
	ds_read_b128 v[172:175], v209 offset:45056
	s_waitcnt lgkmcnt(1)
	v_mfma_f32_32x32x16_bf16 v[82:97], v[138:141], v[148:151], v[82:97]
	v_mfma_f32_32x32x16_bf16 v[18:33], v[138:141], v[152:155], v[18:33]
	s_waitcnt lgkmcnt(0)
	v_mfma_f32_32x32x16_bf16 v[66:81], v[172:175], v[148:151], v[66:81]
	v_mfma_f32_32x32x16_bf16 v[2:17], v[172:175], v[152:155], v[2:17]
	ds_read_b128 v[138:141], v211 offset:32768
	ds_read_b128 v[148:151], v210
	ds_read_b128 v[152:155], v210 offset:4096
	ds_read_b128 v[172:175], v211 offset:36864
	s_waitcnt lgkmcnt(2)
	v_mfma_f32_32x32x16_bf16 v[114:129], v[138:141], v[148:151], v[114:129]
	s_waitcnt lgkmcnt(1)
	v_mfma_f32_32x32x16_bf16 v[50:65], v[138:141], v[152:155], v[50:65]
	s_waitcnt lgkmcnt(0)
	v_mfma_f32_32x32x16_bf16 v[98:113], v[172:175], v[148:151], v[98:113]
	v_mfma_f32_32x32x16_bf16 v[34:49], v[172:175], v[152:155], v[34:49]
	ds_read_b128 v[138:141], v211 offset:40960
	ds_read_b128 v[172:175], v211 offset:45056
	s_waitcnt lgkmcnt(1)
	v_mfma_f32_32x32x16_bf16 v[82:97], v[138:141], v[148:151], v[82:97]
	v_mfma_f32_32x32x16_bf16 v[18:33], v[138:141], v[152:155], v[18:33]
	s_waitcnt lgkmcnt(0)
	v_mfma_f32_32x32x16_bf16 v[66:81], v[172:175], v[148:151], v[66:81]
	s_barrier
; #define G_LOAD(AG, BG, kt, RA, RB) do { const int k0_ = (kt) * 64; int ac_ = k0_; if (g.remap) ac_ = k0_ < 512 ? k0_ : (k0_ < 1024 ? g.seg2 + k0_ - 512 : 2304 + k0_ - 1024); \
;     _Pragma("unroll") for (int i = 0; i < 4; ++i) { RA[i] = *(const u32x4*)(AG + (size_t)(64 * i) * g.lda + ac_); RB[i] = *(const u32x4*)(BG + (size_t)(64 * i) * g.K + k0_); } } while (0)
; #define G_WRITE(buf, RA, RB) do { _Pragma("unroll") for (int i = 0; i < 4; ++i) { *(u32x4*)(lds + (buf) * 65536 + i * 8192 + soff) = RA[i]; *(u32x4*)(lds + (buf) * 65536 + 32768 + i * 8192 + soff) = RB[i]; } } while (0)
; template <int EPI>
; DI void gemm_phase(char* lds, const Params& p, const GemmDesc g, int layer) {
;     ...
;     for (int kt = 0; kt < nk; kt += 2) {
;       const bool last = kt + 2 >= nk;
;       G_WRITE(1, ra0, rb0);
;       if (!last) G_LOAD(Ag, Bg, kt + 2, ra0, rb0); else if (has_next) G_LOAD(Agn, Bgn, 0, ra0, rb0);
;       G_COMPUTE(0);
;       __syncthreads();
;       if (!last || has_next) G_WRITE(0, ra0, rb0);
;       if (!last) G_LOAD(Ag, Bg, kt + 3, ra0, rb0); else if (has_next) G_LOAD(Agn, Bgn, 1, ra0, rb0);
;       G_COMPUTE(1);
;       __syncthreads();
	s_waitcnt vmcnt(6)
	ds_write_b128 v201, v[176:179]
	ds_write_b128 v201, v[236:239] offset:32768
	s_waitcnt vmcnt(5)
	ds_write_b128 v201, v[180:183] offset:8192
	s_waitcnt vmcnt(4)
	ds_write_b128 v201, v[184:187] offset:40960
	s_waitcnt vmcnt(2)
	ds_write_b128 v201, v[192:195] offset:16384
	ds_write_b128 v201, v[188:191] offset:49152
	s_waitcnt vmcnt(1)
	ds_write_b128 v201, v[196:199] offset:24576
	s_waitcnt vmcnt(0)
	ds_write_b128 v201, v[240:243] offset:57344
	global_load_dwordx4 v[236:239], v[132:133], off offset:1408
	global_load_dwordx4 v[176:179], v[130:131], off offset:1408
	global_load_dwordx4 v[180:183], v[170:171], off offset:1408
	global_load_dwordx4 v[184:187], v[142:143], off offset:1408
	global_load_dwordx4 v[188:191], v[136:137], off offset:1408
	global_load_dwordx4 v[192:195], v[134:135], off offset:1408
	global_load_dwordx4 v[196:199], v[146:147], off offset:1408
	global_load_dwordx4 v[240:243], v[158:159], off offset:1408
	v_mfma_f32_32x32x16_bf16 v[2:17], v[172:175], v[152:155], v[2:17]
	ds_read_b128 v[138:141], v223
	ds_read_b128 v[148:151], v222
	ds_read_b128 v[152:155], v222 offset:4096
	ds_read_b128 v[172:175], v223 offset:4096
	s_waitcnt lgkmcnt(2)
	v_mfma_f32_32x32x16_bf16 v[114:129], v[138:141], v[148:151], v[114:129]
	s_waitcnt lgkmcnt(1)
	v_mfma_f32_32x32x16_bf16 v[50:65], v[138:141], v[152:155], v[50:65]
	s_waitcnt lgkmcnt(0)
	v_mfma_f32_32x32x16_bf16 v[98:113], v[172:175], v[148:151], v[98:113]
	v_mfma_f32_32x32x16_bf16 v[34:49], v[172:175], v[152:155], v[34:49]
	ds_read_b128 v[138:141], v223 offset:8192
	ds_read_b128 v[172:175], v223 offset:12288
	s_waitcnt lgkmcnt(1)
	v_mfma_f32_32x32x16_bf16 v[82:97], v[138:141], v[148:151], v[82:97]
	v_mfma_f32_32x32x16_bf16 v[18:33], v[138:141], v[152:155], v[18:33]
	s_waitcnt lgkmcnt(0)
	v_mfma_f32_32x32x16_bf16 v[66:81], v[172:175], v[148:151], v[66:81]
	v_mfma_f32_32x32x16_bf16 v[2:17], v[172:175], v[152:155], v[2:17]
	ds_read_b128 v[138:141], v225
	ds_read_b128 v[148:151], v224
	ds_read_b128 v[152:155], v224 offset:4096
	ds_read_b128 v[172:175], v225 offset:4096
	s_waitcnt lgkmcnt(2)
	v_mfma_f32_32x32x16_bf16 v[114:129], v[138:141], v[148:151], v[114:129]
	s_waitcnt lgkmcnt(1)
	v_mfma_f32_32x32x16_bf16 v[50:65], v[138:141], v[152:155], v[50:65]
	s_waitcnt lgkmcnt(0)
	v_mfma_f32_32x32x16_bf16 v[98:113], v[172:175], v[148:151], v[98:113]
	v_mfma_f32_32x32x16_bf16 v[34:49], v[172:175], v[152:155], v[34:49]
	ds_read_b128 v[138:141], v225 offset:8192
	ds_read_b128 v[172:175], v225 offset:12288
	s_waitcnt lgkmcnt(1)
	v_mfma_f32_32x32x16_bf16 v[82:97], v[138:141], v[148:151], v[82:97]
	v_mfma_f32_32x32x16_bf16 v[18:33], v[138:141], v[152:155], v[18:33]
	s_waitcnt lgkmcnt(0)
	v_mfma_f32_32x32x16_bf16 v[66:81], v[172:175], v[148:151], v[66:81]
	v_mfma_f32_32x32x16_bf16 v[2:17], v[172:175], v[152:155], v[2:17]
	ds_read_b128 v[138:141], v227
	ds_read_b128 v[148:151], v226
	ds_read_b128 v[152:155], v226 offset:4096
	ds_read_b128 v[172:175], v227 offset:4096
	s_waitcnt lgkmcnt(2)
	v_mfma_f32_32x32x16_bf16 v[114:129], v[138:141], v[148:151], v[114:129]
	s_waitcnt lgkmcnt(1)
	v_mfma_f32_32x32x16_bf16 v[50:65], v[138:141], v[152:155], v[50:65]
	s_waitcnt lgkmcnt(0)
	v_mfma_f32_32x32x16_bf16 v[98:113], v[172:175], v[148:151], v[98:113]
	v_mfma_f32_32x32x16_bf16 v[34:49], v[172:175], v[152:155], v[34:49]
	ds_read_b128 v[138:141], v227 offset:8192
	ds_read_b128 v[172:175], v227 offset:12288
	s_waitcnt lgkmcnt(1)
	v_mfma_f32_32x32x16_bf16 v[82:97], v[138:141], v[148:151], v[82:97]
	v_mfma_f32_32x32x16_bf16 v[18:33], v[138:141], v[152:155], v[18:33]
	s_waitcnt lgkmcnt(0)
	v_mfma_f32_32x32x16_bf16 v[66:81], v[172:175], v[148:151], v[66:81]
	v_mfma_f32_32x32x16_bf16 v[2:17], v[172:175], v[152:155], v[2:17]
	ds_read_b128 v[138:141], v229
	ds_read_b128 v[148:151], v228
	ds_read_b128 v[152:155], v228 offset:4096
	ds_read_b128 v[172:175], v229 offset:4096
	s_waitcnt lgkmcnt(2)
	v_mfma_f32_32x32x16_bf16 v[114:129], v[138:141], v[148:151], v[114:129]
	s_waitcnt lgkmcnt(1)
	v_mfma_f32_32x32x16_bf16 v[50:65], v[138:141], v[152:155], v[50:65]
	s_waitcnt lgkmcnt(0)
	v_mfma_f32_32x32x16_bf16 v[98:113], v[172:175], v[148:151], v[98:113]
	v_mfma_f32_32x32x16_bf16 v[34:49], v[172:175], v[152:155], v[34:49]
	ds_read_b128 v[138:141], v229 offset:8192
	ds_read_b128 v[172:175], v229 offset:12288
	s_waitcnt lgkmcnt(1)
	v_mfma_f32_32x32x16_bf16 v[82:97], v[138:141], v[148:151], v[82:97]
	v_mfma_f32_32x32x16_bf16 v[18:33], v[138:141], v[152:155], v[18:33]
	s_waitcnt lgkmcnt(0)
	v_mfma_f32_32x32x16_bf16 v[66:81], v[172:175], v[148:151], v[66:81]
	s_barrier
; #define G_LOAD(AG, BG, kt, RA, RB) do { const int k0_ = (kt) * 64; int ac_ = k0_; if (g.remap) ac_ = k0_ < 512 ? k0_ : (k0_ < 1024 ? g.seg2 + k0_ - 512 : 2304 + k0_ - 1024); \
;     _Pragma("unroll") for (int i = 0; i < 4; ++i) { RA[i] = *(const u32x4*)(AG + (size_t)(64 * i) * g.lda + ac_); RB[i] = *(const u32x4*)(BG + (size_t)(64 * i) * g.K + k0_); } } while (0)
; #define G_WRITE(buf, RA, RB) do { _Pragma("unroll") for (int i = 0; i < 4; ++i) { *(u32x4*)(lds + (buf) * 65536 + i * 8192 + soff) = RA[i]; *(u32x4*)(lds + (buf) * 65536 + 32768 + i * 8192 + soff) = RB[i]; } } while (0)
; template <int EPI>
; DI void gemm_phase(char* lds, const Params& p, const GemmDesc g, int layer) {
;     ...
;       const bool last = kt + 2 >= nk;
;       G_WRITE(1, ra0, rb0);
;       if (!last) G_LOAD(Ag, Bg, kt + 2, ra0, rb0); else if (has_next) G_LOAD(Agn, Bgn, 0, ra0, rb0);
;       G_COMPUTE(0);
;       __syncthreads();
;       if (!last || has_next) G_WRITE(0, ra0, rb0);
;       if (!last) G_LOAD(Ag, Bg, kt + 3, ra0, rb0); else if (has_next) G_LOAD(Agn, Bgn, 1, ra0, rb0);
;       G_COMPUTE(1);
;       __syncthreads();
	s_waitcnt vmcnt(6)
	ds_write_b128 v202, v[176:179]
	s_waitcnt vmcnt(5)
	ds_write_b128 v203, v[180:183]
	ds_write_b128 v202, v[236:239] offset:8192
	s_waitcnt vmcnt(4)
	ds_write_b128 v203, v[184:187] offset:8192
	s_waitcnt vmcnt(2)
	ds_write_b128 v202, v[192:195] offset:16384
	s_waitcnt vmcnt(1)
	ds_write_b128 v203, v[196:199] offset:16384
	ds_write_b128 v202, v[188:191] offset:24576
	s_waitcnt vmcnt(0)
	ds_write_b128 v203, v[240:243] offset:24576
	global_load_dwordx4 v[236:239], v[170:171], off offset:1536
	global_load_dwordx4 v[176:179], v[130:131], off offset:1536
	global_load_dwordx4 v[180:183], v[132:133], off offset:1536
	global_load_dwordx4 v[184:187], v[142:143], off offset:1536
	global_load_dwordx4 v[188:191], v[146:147], off offset:1536
	global_load_dwordx4 v[192:195], v[134:135], off offset:1536
	global_load_dwordx4 v[196:199], v[136:137], off offset:1536
	global_load_dwordx4 v[240:243], v[158:159], off offset:1536
	v_mfma_f32_32x32x16_bf16 v[2:17], v[172:175], v[152:155], v[2:17]
	ds_read_b128 v[138:141], v205 offset:32768
	ds_read_b128 v[148:151], v204
	ds_read_b128 v[152:155], v204 offset:4096
	ds_read_b128 v[172:175], v205 offset:36864
	s_waitcnt lgkmcnt(2)
	v_mfma_f32_32x32x16_bf16 v[114:129], v[138:141], v[148:151], v[114:129]
	s_waitcnt lgkmcnt(1)
	v_mfma_f32_32x32x16_bf16 v[50:65], v[138:141], v[152:155], v[50:65]
	s_waitcnt lgkmcnt(0)
	v_mfma_f32_32x32x16_bf16 v[98:113], v[172:175], v[148:151], v[98:113]
	v_mfma_f32_32x32x16_bf16 v[34:49], v[172:175], v[152:155], v[34:49]
	ds_read_b128 v[138:141], v205 offset:40960
	ds_read_b128 v[172:175], v205 offset:45056
	s_waitcnt lgkmcnt(1)
	v_mfma_f32_32x32x16_bf16 v[82:97], v[138:141], v[148:151], v[82:97]
	v_mfma_f32_32x32x16_bf16 v[18:33], v[138:141], v[152:155], v[18:33]
	s_waitcnt lgkmcnt(0)
	v_mfma_f32_32x32x16_bf16 v[66:81], v[172:175], v[148:151], v[66:81]
	v_mfma_f32_32x32x16_bf16 v[2:17], v[172:175], v[152:155], v[2:17]
	ds_read_b128 v[138:141], v207 offset:32768
	ds_read_b128 v[148:151], v206
	ds_read_b128 v[152:155], v206 offset:4096
	ds_read_b128 v[172:175], v207 offset:36864
	s_waitcnt lgkmcnt(2)
	v_mfma_f32_32x32x16_bf16 v[114:129], v[138:141], v[148:151], v[114:129]
	s_waitcnt lgkmcnt(1)
	v_mfma_f32_32x32x16_bf16 v[50:65], v[138:141], v[152:155], v[50:65]
	s_waitcnt lgkmcnt(0)
	v_mfma_f32_32x32x16_bf16 v[98:113], v[172:175], v[148:151], v[98:113]
	v_mfma_f32_32x32x16_bf16 v[34:49], v[172:175], v[152:155], v[34:49]
	ds_read_b128 v[138:141], v207 offset:40960
	ds_read_b128 v[172:175], v207 offset:45056
	s_waitcnt lgkmcnt(1)
	v_mfma_f32_32x32x16_bf16 v[82:97], v[138:141], v[148:151], v[82:97]
	v_mfma_f32_32x32x16_bf16 v[18:33], v[138:141], v[152:155], v[18:33]
	s_waitcnt lgkmcnt(0)
	v_mfma_f32_32x32x16_bf16 v[66:81], v[172:175], v[148:151], v[66:81]
	v_mfma_f32_32x32x16_bf16 v[2:17], v[172:175], v[152:155], v[2:17]
	ds_read_b128 v[138:141], v209 offset:32768
	ds_read_b128 v[148:151], v208
	ds_read_b128 v[152:155], v208 offset:4096
	ds_read_b128 v[172:175], v209 offset:36864
	s_waitcnt lgkmcnt(2)
	v_mfma_f32_32x32x16_bf16 v[114:129], v[138:141], v[148:151], v[114:129]
	s_waitcnt lgkmcnt(1)
	v_mfma_f32_32x32x16_bf16 v[50:65], v[138:141], v[152:155], v[50:65]
	s_waitcnt lgkmcnt(0)
	v_mfma_f32_32x32x16_bf16 v[98:113], v[172:175], v[148:151], v[98:113]
	v_mfma_f32_32x32x16_bf16 v[34:49], v[172:175], v[152:155], v[34:49]
	ds_read_b128 v[138:141], v209 offset:40960
	ds_read_b128 v[172:175], v209 offset:45056
	s_waitcnt lgkmcnt(1)
	v_mfma_f32_32x32x16_bf16 v[82:97], v[138:141], v[148:151], v[82:97]
	v_mfma_f32_32x32x16_bf16 v[18:33], v[138:141], v[152:155], v[18:33]
	s_waitcnt lgkmcnt(0)
	v_mfma_f32_32x32x16_bf16 v[66:81], v[172:175], v[148:151], v[66:81]
	v_mfma_f32_32x32x16_bf16 v[2:17], v[172:175], v[152:155], v[2:17]
	ds_read_b128 v[138:141], v211 offset:32768
	ds_read_b128 v[148:151], v210
	ds_read_b128 v[152:155], v210 offset:4096
	ds_read_b128 v[172:175], v211 offset:36864
	s_waitcnt lgkmcnt(2)
	v_mfma_f32_32x32x16_bf16 v[114:129], v[138:141], v[148:151], v[114:129]
	s_waitcnt lgkmcnt(1)
	v_mfma_f32_32x32x16_bf16 v[50:65], v[138:141], v[152:155], v[50:65]
	s_waitcnt lgkmcnt(0)
	v_mfma_f32_32x32x16_bf16 v[98:113], v[172:175], v[148:151], v[98:113]
	v_mfma_f32_32x32x16_bf16 v[34:49], v[172:175], v[152:155], v[34:49]
	ds_read_b128 v[138:141], v211 offset:40960
	ds_read_b128 v[172:175], v211 offset:45056
	s_waitcnt lgkmcnt(1)
	v_mfma_f32_32x32x16_bf16 v[82:97], v[138:141], v[148:151], v[82:97]
	v_mfma_f32_32x32x16_bf16 v[18:33], v[138:141], v[152:155], v[18:33]
	s_waitcnt lgkmcnt(0)
	v_mfma_f32_32x32x16_bf16 v[66:81], v[172:175], v[148:151], v[66:81]
	s_barrier
; #define G_LOAD(AG, BG, kt, RA, RB) do { const int k0_ = (kt) * 64; int ac_ = k0_; if (g.remap) ac_ = k0_ < 512 ? k0_ : (k0_ < 1024 ? g.seg2 + k0_ - 512 : 2304 + k0_ - 1024); \
;     _Pragma("unroll") for (int i = 0; i < 4; ++i) { RA[i] = *(const u32x4*)(AG + (size_t)(64 * i) * g.lda + ac_); RB[i] = *(const u32x4*)(BG + (size_t)(64 * i) * g.K + k0_); } } while (0)
; #define G_WRITE(buf, RA, RB) do { _Pragma("unroll") for (int i = 0; i < 4; ++i) { *(u32x4*)(lds + (buf) * 65536 + i * 8192 + soff) = RA[i]; *(u32x4*)(lds + (buf) * 65536 + 32768 + i * 8192 + soff) = RB[i]; } } while (0)
; template <int EPI>
; DI void gemm_phase(char* lds, const Params& p, const GemmDesc g, int layer) {
;     ...
;       const bool last = kt + 2 >= nk;
;       G_WRITE(1, ra0, rb0);
;       if (!last) G_LOAD(Ag, Bg, kt + 2, ra0, rb0); else if (has_next) G_LOAD(Agn, Bgn, 0, ra0, rb0);
;       G_COMPUTE(0);
;       __syncthreads();
;       if (!last || has_next) G_WRITE(0, ra0, rb0);
;       if (!last) G_LOAD(Ag, Bg, kt + 3, ra0, rb0); else if (has_next) G_LOAD(Agn, Bgn, 1, ra0, rb0);
;       G_COMPUTE(1);
;       __syncthreads();
	s_waitcnt vmcnt(6)
	ds_write_b128 v201, v[176:179]
	ds_write_b128 v201, v[236:239] offset:32768
	s_waitcnt vmcnt(5)
	ds_write_b128 v201, v[180:183] offset:8192
	s_waitcnt vmcnt(4)
	ds_write_b128 v201, v[184:187] offset:40960
	s_waitcnt vmcnt(2)
	ds_write_b128 v201, v[192:195] offset:16384
	ds_write_b128 v201, v[188:191] offset:49152
	s_waitcnt vmcnt(1)
	ds_write_b128 v201, v[196:199] offset:24576
	s_waitcnt vmcnt(0)
	ds_write_b128 v201, v[240:243] offset:57344
	global_load_dwordx4 v[236:239], v[132:133], off offset:1664
	global_load_dwordx4 v[176:179], v[130:131], off offset:1664
	global_load_dwordx4 v[180:183], v[170:171], off offset:1664
	global_load_dwordx4 v[184:187], v[142:143], off offset:1664
	global_load_dwordx4 v[188:191], v[136:137], off offset:1664
	global_load_dwordx4 v[192:195], v[134:135], off offset:1664
	global_load_dwordx4 v[196:199], v[146:147], off offset:1664
	global_load_dwordx4 v[240:243], v[158:159], off offset:1664
	v_mfma_f32_32x32x16_bf16 v[2:17], v[172:175], v[152:155], v[2:17]
	ds_read_b128 v[138:141], v223
	ds_read_b128 v[148:151], v222
	ds_read_b128 v[152:155], v222 offset:4096
	ds_read_b128 v[172:175], v223 offset:4096
	s_waitcnt lgkmcnt(2)
	v_mfma_f32_32x32x16_bf16 v[114:129], v[138:141], v[148:151], v[114:129]
	s_waitcnt lgkmcnt(1)
	v_mfma_f32_32x32x16_bf16 v[50:65], v[138:141], v[152:155], v[50:65]
	s_waitcnt lgkmcnt(0)
	v_mfma_f32_32x32x16_bf16 v[98:113], v[172:175], v[148:151], v[98:113]
	v_mfma_f32_32x32x16_bf16 v[34:49], v[172:175], v[152:155], v[34:49]
	ds_read_b128 v[138:141], v223 offset:8192
	ds_read_b128 v[172:175], v223 offset:12288
	s_waitcnt lgkmcnt(1)
	v_mfma_f32_32x32x16_bf16 v[82:97], v[138:141], v[148:151], v[82:97]
	v_mfma_f32_32x32x16_bf16 v[18:33], v[138:141], v[152:155], v[18:33]
	s_waitcnt lgkmcnt(0)
	v_mfma_f32_32x32x16_bf16 v[66:81], v[172:175], v[148:151], v[66:81]
	v_mfma_f32_32x32x16_bf16 v[2:17], v[172:175], v[152:155], v[2:17]
	ds_read_b128 v[138:141], v225
	ds_read_b128 v[148:151], v224
	ds_read_b128 v[152:155], v224 offset:4096
	ds_read_b128 v[172:175], v225 offset:4096
	s_waitcnt lgkmcnt(2)
	v_mfma_f32_32x32x16_bf16 v[114:129], v[138:141], v[148:151], v[114:129]
	s_waitcnt lgkmcnt(1)
	v_mfma_f32_32x32x16_bf16 v[50:65], v[138:141], v[152:155], v[50:65]
	s_waitcnt lgkmcnt(0)
	v_mfma_f32_32x32x16_bf16 v[98:113], v[172:175], v[148:151], v[98:113]
	v_mfma_f32_32x32x16_bf16 v[34:49], v[172:175], v[152:155], v[34:49]
	ds_read_b128 v[138:141], v225 offset:8192
	ds_read_b128 v[172:175], v225 offset:12288
	s_waitcnt lgkmcnt(1)
	v_mfma_f32_32x32x16_bf16 v[82:97], v[138:141], v[148:151], v[82:97]
	v_mfma_f32_32x32x16_bf16 v[18:33], v[138:141], v[152:155], v[18:33]
	s_waitcnt lgkmcnt(0)
	v_mfma_f32_32x32x16_bf16 v[66:81], v[172:175], v[148:151], v[66:81]
	v_mfma_f32_32x32x16_bf16 v[2:17], v[172:175], v[152:155], v[2:17]
	ds_read_b128 v[138:141], v227
	ds_read_b128 v[148:151], v226
	ds_read_b128 v[152:155], v226 offset:4096
	ds_read_b128 v[172:175], v227 offset:4096
	s_waitcnt lgkmcnt(2)
	v_mfma_f32_32x32x16_bf16 v[114:129], v[138:141], v[148:151], v[114:129]
	s_waitcnt lgkmcnt(1)
	v_mfma_f32_32x32x16_bf16 v[50:65], v[138:141], v[152:155], v[50:65]
	s_waitcnt lgkmcnt(0)
	v_mfma_f32_32x32x16_bf16 v[98:113], v[172:175], v[148:151], v[98:113]
	v_mfma_f32_32x32x16_bf16 v[34:49], v[172:175], v[152:155], v[34:49]
	ds_read_b128 v[138:141], v227 offset:8192
	ds_read_b128 v[172:175], v227 offset:12288
	s_waitcnt lgkmcnt(1)
	v_mfma_f32_32x32x16_bf16 v[82:97], v[138:141], v[148:151], v[82:97]
	v_mfma_f32_32x32x16_bf16 v[18:33], v[138:141], v[152:155], v[18:33]
	s_waitcnt lgkmcnt(0)
	v_mfma_f32_32x32x16_bf16 v[66:81], v[172:175], v[148:151], v[66:81]
	v_mfma_f32_32x32x16_bf16 v[2:17], v[172:175], v[152:155], v[2:17]
	ds_read_b128 v[138:141], v229
	ds_read_b128 v[148:151], v228
	ds_read_b128 v[152:155], v228 offset:4096
	ds_read_b128 v[172:175], v229 offset:4096
	s_waitcnt lgkmcnt(2)
	v_mfma_f32_32x32x16_bf16 v[114:129], v[138:141], v[148:151], v[114:129]
	s_waitcnt lgkmcnt(1)
	v_mfma_f32_32x32x16_bf16 v[50:65], v[138:141], v[152:155], v[50:65]
	s_waitcnt lgkmcnt(0)
	v_mfma_f32_32x32x16_bf16 v[98:113], v[172:175], v[148:151], v[98:113]
	v_mfma_f32_32x32x16_bf16 v[34:49], v[172:175], v[152:155], v[34:49]
	ds_read_b128 v[138:141], v229 offset:8192
	ds_read_b128 v[172:175], v229 offset:12288
	s_waitcnt lgkmcnt(1)
	v_mfma_f32_32x32x16_bf16 v[82:97], v[138:141], v[148:151], v[82:97]
	v_mfma_f32_32x32x16_bf16 v[18:33], v[138:141], v[152:155], v[18:33]
	s_waitcnt lgkmcnt(0)
	v_mfma_f32_32x32x16_bf16 v[66:81], v[172:175], v[148:151], v[66:81]
	s_barrier
; #define G_LOAD(AG, BG, kt, RA, RB) do { const int k0_ = (kt) * 64; int ac_ = k0_; if (g.remap) ac_ = k0_ < 512 ? k0_ : (k0_ < 1024 ? g.seg2 + k0_ - 512 : 2304 + k0_ - 1024); \
;     _Pragma("unroll") for (int i = 0; i < 4; ++i) { RA[i] = *(const u32x4*)(AG + (size_t)(64 * i) * g.lda + ac_); RB[i] = *(const u32x4*)(BG + (size_t)(64 * i) * g.K + k0_); } } while (0)
; #define G_WRITE(buf, RA, RB) do { _Pragma("unroll") for (int i = 0; i < 4; ++i) { *(u32x4*)(lds + (buf) * 65536 + i * 8192 + soff) = RA[i]; *(u32x4*)(lds + (buf) * 65536 + 32768 + i * 8192 + soff) = RB[i]; } } while (0)
; template <int EPI>
; DI void gemm_phase(char* lds, const Params& p, const GemmDesc g, int layer) {
;     ...
;       const bool last = kt + 2 >= nk;
;       G_WRITE(1, ra0, rb0);
;       if (!last) G_LOAD(Ag, Bg, kt + 2, ra0, rb0); else if (has_next) G_LOAD(Agn, Bgn, 0, ra0, rb0);
;       G_COMPUTE(0);
;       __syncthreads();
;       if (!last || has_next) G_WRITE(0, ra0, rb0);
;       if (!last) G_LOAD(Ag, Bg, kt + 3, ra0, rb0); else if (has_next) G_LOAD(Agn, Bgn, 1, ra0, rb0);
;       G_COMPUTE(1);
;       __syncthreads();
	s_waitcnt vmcnt(6)
	ds_write_b128 v202, v[176:179]
	s_waitcnt vmcnt(5)
	ds_write_b128 v203, v[180:183]
	ds_write_b128 v202, v[236:239] offset:8192
	s_waitcnt vmcnt(4)
	ds_write_b128 v203, v[184:187] offset:8192
	s_waitcnt vmcnt(2)
	ds_write_b128 v202, v[192:195] offset:16384
	s_waitcnt vmcnt(1)
	ds_write_b128 v203, v[196:199] offset:16384
	ds_write_b128 v202, v[188:191] offset:24576
	s_waitcnt vmcnt(0)
	ds_write_b128 v203, v[240:243] offset:24576
	global_load_dwordx4 v[236:239], v[170:171], off offset:1792
	global_load_dwordx4 v[176:179], v[130:131], off offset:1792
	global_load_dwordx4 v[180:183], v[132:133], off offset:1792
	global_load_dwordx4 v[184:187], v[142:143], off offset:1792
	global_load_dwordx4 v[188:191], v[146:147], off offset:1792
	global_load_dwordx4 v[192:195], v[134:135], off offset:1792
	global_load_dwordx4 v[196:199], v[136:137], off offset:1792
	global_load_dwordx4 v[240:243], v[158:159], off offset:1792
	v_mfma_f32_32x32x16_bf16 v[2:17], v[172:175], v[152:155], v[2:17]
	ds_read_b128 v[138:141], v205 offset:32768
	ds_read_b128 v[148:151], v204
	ds_read_b128 v[152:155], v204 offset:4096
	ds_read_b128 v[172:175], v205 offset:36864
	s_waitcnt lgkmcnt(2)
	v_mfma_f32_32x32x16_bf16 v[114:129], v[138:141], v[148:151], v[114:129]
	s_waitcnt lgkmcnt(1)
	v_mfma_f32_32x32x16_bf16 v[50:65], v[138:141], v[152:155], v[50:65]
	s_waitcnt lgkmcnt(0)
	v_mfma_f32_32x32x16_bf16 v[98:113], v[172:175], v[148:151], v[98:113]
	v_mfma_f32_32x32x16_bf16 v[34:49], v[172:175], v[152:155], v[34:49]
	ds_read_b128 v[138:141], v205 offset:40960
	ds_read_b128 v[172:175], v205 offset:45056
	s_waitcnt lgkmcnt(1)
	v_mfma_f32_32x32x16_bf16 v[82:97], v[138:141], v[148:151], v[82:97]
	v_mfma_f32_32x32x16_bf16 v[18:33], v[138:141], v[152:155], v[18:33]
	s_waitcnt lgkmcnt(0)
	v_mfma_f32_32x32x16_bf16 v[66:81], v[172:175], v[148:151], v[66:81]
	v_mfma_f32_32x32x16_bf16 v[2:17], v[172:175], v[152:155], v[2:17]
	ds_read_b128 v[138:141], v207 offset:32768
	ds_read_b128 v[148:151], v206
	ds_read_b128 v[152:155], v206 offset:4096
	ds_read_b128 v[172:175], v207 offset:36864
	s_waitcnt lgkmcnt(2)
	v_mfma_f32_32x32x16_bf16 v[114:129], v[138:141], v[148:151], v[114:129]
	s_waitcnt lgkmcnt(1)
	v_mfma_f32_32x32x16_bf16 v[50:65], v[138:141], v[152:155], v[50:65]
	s_waitcnt lgkmcnt(0)
	v_mfma_f32_32x32x16_bf16 v[98:113], v[172:175], v[148:151], v[98:113]
	v_mfma_f32_32x32x16_bf16 v[34:49], v[172:175], v[152:155], v[34:49]
	ds_read_b128 v[138:141], v207 offset:40960
	ds_read_b128 v[172:175], v207 offset:45056
	s_waitcnt lgkmcnt(1)
	v_mfma_f32_32x32x16_bf16 v[82:97], v[138:141], v[148:151], v[82:97]
	v_mfma_f32_32x32x16_bf16 v[18:33], v[138:141], v[152:155], v[18:33]
	s_waitcnt lgkmcnt(0)
	v_mfma_f32_32x32x16_bf16 v[66:81], v[172:175], v[148:151], v[66:81]
	v_mfma_f32_32x32x16_bf16 v[2:17], v[172:175], v[152:155], v[2:17]
	ds_read_b128 v[138:141], v209 offset:32768
	ds_read_b128 v[148:151], v208
	ds_read_b128 v[152:155], v208 offset:4096
	ds_read_b128 v[172:175], v209 offset:36864
	s_waitcnt lgkmcnt(2)
	v_mfma_f32_32x32x16_bf16 v[114:129], v[138:141], v[148:151], v[114:129]
	s_waitcnt lgkmcnt(1)
	v_mfma_f32_32x32x16_bf16 v[50:65], v[138:141], v[152:155], v[50:65]
	s_waitcnt lgkmcnt(0)
	v_mfma_f32_32x32x16_bf16 v[98:113], v[172:175], v[148:151], v[98:113]
	v_mfma_f32_32x32x16_bf16 v[34:49], v[172:175], v[152:155], v[34:49]
	ds_read_b128 v[138:141], v209 offset:40960
	ds_read_b128 v[172:175], v209 offset:45056
	s_waitcnt lgkmcnt(1)
	v_mfma_f32_32x32x16_bf16 v[82:97], v[138:141], v[148:151], v[82:97]
	v_mfma_f32_32x32x16_bf16 v[18:33], v[138:141], v[152:155], v[18:33]
	s_waitcnt lgkmcnt(0)
	v_mfma_f32_32x32x16_bf16 v[66:81], v[172:175], v[148:151], v[66:81]
	v_mfma_f32_32x32x16_bf16 v[2:17], v[172:175], v[152:155], v[2:17]
	ds_read_b128 v[138:141], v211 offset:32768
	ds_read_b128 v[148:151], v210
	ds_read_b128 v[152:155], v210 offset:4096
	ds_read_b128 v[172:175], v211 offset:36864
	s_waitcnt lgkmcnt(2)
	v_mfma_f32_32x32x16_bf16 v[114:129], v[138:141], v[148:151], v[114:129]
	s_waitcnt lgkmcnt(1)
	v_mfma_f32_32x32x16_bf16 v[50:65], v[138:141], v[152:155], v[50:65]
	s_waitcnt lgkmcnt(0)
	v_mfma_f32_32x32x16_bf16 v[98:113], v[172:175], v[148:151], v[98:113]
	v_mfma_f32_32x32x16_bf16 v[34:49], v[172:175], v[152:155], v[34:49]
	ds_read_b128 v[138:141], v211 offset:40960
	ds_read_b128 v[172:175], v211 offset:45056
	s_waitcnt lgkmcnt(1)
	v_mfma_f32_32x32x16_bf16 v[82:97], v[138:141], v[148:151], v[82:97]
	v_mfma_f32_32x32x16_bf16 v[18:33], v[138:141], v[152:155], v[18:33]
	s_waitcnt lgkmcnt(0)
	v_mfma_f32_32x32x16_bf16 v[66:81], v[172:175], v[148:151], v[66:81]
	s_barrier
; #define G_LOAD(AG, BG, kt, RA, RB) do { const int k0_ = (kt) * 64; int ac_ = k0_; if (g.remap) ac_ = k0_ < 512 ? k0_ : (k0_ < 1024 ? g.seg2 + k0_ - 512 : 2304 + k0_ - 1024); \
;     _Pragma("unroll") for (int i = 0; i < 4; ++i) { RA[i] = *(const u32x4*)(AG + (size_t)(64 * i) * g.lda + ac_); RB[i] = *(const u32x4*)(BG + (size_t)(64 * i) * g.K + k0_); } } while (0)
; #define G_WRITE(buf, RA, RB) do { _Pragma("unroll") for (int i = 0; i < 4; ++i) { *(u32x4*)(lds + (buf) * 65536 + i * 8192 + soff) = RA[i]; *(u32x4*)(lds + (buf) * 65536 + 32768 + i * 8192 + soff) = RB[i]; } } while (0)
; template <int EPI>
; DI void gemm_phase(char* lds, const Params& p, const GemmDesc g, int layer) {
;     ...
;       const bool last = kt + 2 >= nk;
;       G_WRITE(1, ra0, rb0);
;       if (!last) G_LOAD(Ag, Bg, kt + 2, ra0, rb0); else if (has_next) G_LOAD(Agn, Bgn, 0, ra0, rb0);
;       G_COMPUTE(0);
;       __syncthreads();
;       if (!last || has_next) G_WRITE(0, ra0, rb0);
;       if (!last) G_LOAD(Ag, Bg, kt + 3, ra0, rb0); else if (has_next) G_LOAD(Agn, Bgn, 1, ra0, rb0);
;       G_COMPUTE(1);
;       __syncthreads();
	s_waitcnt vmcnt(6)
	ds_write_b128 v201, v[176:179]
	ds_write_b128 v201, v[236:239] offset:32768
	s_waitcnt vmcnt(5)
	ds_write_b128 v201, v[180:183] offset:8192
	s_waitcnt vmcnt(4)
	ds_write_b128 v201, v[184:187] offset:40960
	s_waitcnt vmcnt(2)
	ds_write_b128 v201, v[192:195] offset:16384
	ds_write_b128 v201, v[188:191] offset:49152
	s_waitcnt vmcnt(1)
	ds_write_b128 v201, v[196:199] offset:24576
	s_waitcnt vmcnt(0)
	ds_write_b128 v201, v[240:243] offset:57344
	global_load_dwordx4 v[236:239], v[132:133], off offset:1920
	global_load_dwordx4 v[130:133], v[130:131], off offset:1920
	global_load_dwordx4 v[176:179], v[170:171], off offset:1920
	global_load_dwordx4 v[180:183], v[142:143], off offset:1920
	global_load_dwordx4 v[184:187], v[136:137], off offset:1920
	global_load_dwordx4 v[134:137], v[134:135], off offset:1920
	global_load_dwordx4 v[188:191], v[146:147], off offset:1920
	global_load_dwordx4 v[240:243], v[158:159], off offset:1920
	v_mfma_f32_32x32x16_bf16 v[2:17], v[172:175], v[152:155], v[2:17]
	ds_read_b128 v[138:141], v223
	ds_read_b128 v[148:151], v222
	ds_read_b128 v[152:155], v222 offset:4096
	ds_read_b128 v[172:175], v223 offset:4096
	s_waitcnt lgkmcnt(2)
	v_mfma_f32_32x32x16_bf16 v[114:129], v[138:141], v[148:151], v[114:129]
	s_waitcnt lgkmcnt(1)
	v_mfma_f32_32x32x16_bf16 v[50:65], v[138:141], v[152:155], v[50:65]
	s_waitcnt lgkmcnt(0)
	v_mfma_f32_32x32x16_bf16 v[98:113], v[172:175], v[148:151], v[98:113]
	v_mfma_f32_32x32x16_bf16 v[34:49], v[172:175], v[152:155], v[34:49]
	ds_read_b128 v[138:141], v223 offset:8192
	ds_read_b128 v[172:175], v223 offset:12288
	s_waitcnt lgkmcnt(1)
	v_mfma_f32_32x32x16_bf16 v[82:97], v[138:141], v[148:151], v[82:97]
	v_mfma_f32_32x32x16_bf16 v[18:33], v[138:141], v[152:155], v[18:33]
	s_waitcnt lgkmcnt(0)
	v_mfma_f32_32x32x16_bf16 v[66:81], v[172:175], v[148:151], v[66:81]
	v_mfma_f32_32x32x16_bf16 v[2:17], v[172:175], v[152:155], v[2:17]
	ds_read_b128 v[138:141], v225
	ds_read_b128 v[148:151], v224
	ds_read_b128 v[152:155], v224 offset:4096
	ds_read_b128 v[172:175], v225 offset:4096
	s_waitcnt lgkmcnt(2)
	v_mfma_f32_32x32x16_bf16 v[114:129], v[138:141], v[148:151], v[114:129]
	s_waitcnt lgkmcnt(1)
	v_mfma_f32_32x32x16_bf16 v[50:65], v[138:141], v[152:155], v[50:65]
	s_waitcnt lgkmcnt(0)
	v_mfma_f32_32x32x16_bf16 v[98:113], v[172:175], v[148:151], v[98:113]
	v_mfma_f32_32x32x16_bf16 v[34:49], v[172:175], v[152:155], v[34:49]
	ds_read_b128 v[138:141], v225 offset:8192
	ds_read_b128 v[172:175], v225 offset:12288
	s_waitcnt lgkmcnt(1)
	v_mfma_f32_32x32x16_bf16 v[82:97], v[138:141], v[148:151], v[82:97]
	v_mfma_f32_32x32x16_bf16 v[18:33], v[138:141], v[152:155], v[18:33]
	s_waitcnt lgkmcnt(0)
	v_mfma_f32_32x32x16_bf16 v[66:81], v[172:175], v[148:151], v[66:81]
	v_mfma_f32_32x32x16_bf16 v[2:17], v[172:175], v[152:155], v[2:17]
	ds_read_b128 v[138:141], v227
	ds_read_b128 v[148:151], v226
	ds_read_b128 v[152:155], v226 offset:4096
	ds_read_b128 v[172:175], v227 offset:4096
	s_waitcnt lgkmcnt(2)
	v_mfma_f32_32x32x16_bf16 v[114:129], v[138:141], v[148:151], v[114:129]
	s_waitcnt lgkmcnt(1)
	v_mfma_f32_32x32x16_bf16 v[50:65], v[138:141], v[152:155], v[50:65]
	s_waitcnt lgkmcnt(0)
	v_mfma_f32_32x32x16_bf16 v[98:113], v[172:175], v[148:151], v[98:113]
	v_mfma_f32_32x32x16_bf16 v[34:49], v[172:175], v[152:155], v[34:49]
	ds_read_b128 v[138:141], v227 offset:8192
	ds_read_b128 v[172:175], v227 offset:12288
	s_waitcnt lgkmcnt(1)
	v_mfma_f32_32x32x16_bf16 v[82:97], v[138:141], v[148:151], v[82:97]
	v_mfma_f32_32x32x16_bf16 v[18:33], v[138:141], v[152:155], v[18:33]
	s_waitcnt lgkmcnt(0)
	v_mfma_f32_32x32x16_bf16 v[66:81], v[172:175], v[148:151], v[66:81]
	v_mfma_f32_32x32x16_bf16 v[2:17], v[172:175], v[152:155], v[2:17]
	ds_read_b128 v[138:141], v229
	ds_read_b128 v[148:151], v228
	ds_read_b128 v[152:155], v228 offset:4096
	ds_read_b128 v[172:175], v229 offset:4096
	s_waitcnt lgkmcnt(2)
	v_mfma_f32_32x32x16_bf16 v[114:129], v[138:141], v[148:151], v[114:129]
	s_waitcnt lgkmcnt(1)
	v_mfma_f32_32x32x16_bf16 v[50:65], v[138:141], v[152:155], v[50:65]
	s_waitcnt lgkmcnt(0)
	v_mfma_f32_32x32x16_bf16 v[98:113], v[172:175], v[148:151], v[98:113]
	v_mfma_f32_32x32x16_bf16 v[34:49], v[172:175], v[152:155], v[34:49]
	ds_read_b128 v[138:141], v229 offset:8192
	ds_read_b128 v[172:175], v229 offset:12288
	s_waitcnt lgkmcnt(1)
	v_mfma_f32_32x32x16_bf16 v[82:97], v[138:141], v[148:151], v[82:97]
	v_mfma_f32_32x32x16_bf16 v[18:33], v[138:141], v[152:155], v[18:33]
	s_nop 0
	s_nop 0
	s_nop 0
	s_nop 0
	s_waitcnt lgkmcnt(0)
	v_mfma_f32_32x32x16_bf16 v[66:81], v[172:175], v[148:151], v[66:81]
	s_barrier
; #define G_LOAD(AG, BG, kt, RA, RB) do { const int k0_ = (kt) * 64; int ac_ = k0_; if (g.remap) ac_ = k0_ < 512 ? k0_ : (k0_ < 1024 ? g.seg2 + k0_ - 512 : 2304 + k0_ - 1024); \
;     _Pragma("unroll") for (int i = 0; i < 4; ++i) { RA[i] = *(const u32x4*)(AG + (size_t)(64 * i) * g.lda + ac_); RB[i] = *(const u32x4*)(BG + (size_t)(64 * i) * g.K + k0_); } } while (0)
; #define G_WRITE(buf, RA, RB) do { _Pragma("unroll") for (int i = 0; i < 4; ++i) { *(u32x4*)(lds + (buf) * 65536 + i * 8192 + soff) = RA[i]; *(u32x4*)(lds + (buf) * 65536 + 32768 + i * 8192 + soff) = RB[i]; } } while (0)
; template <int EPI>
; DI void gemm_phase(char* lds, const Params& p, const GemmDesc g, int layer) {
;     ...
;       const bool last = kt + 2 >= nk;
;       G_WRITE(1, ra0, rb0);
;       if (!last) G_LOAD(Ag, Bg, kt + 2, ra0, rb0); else if (has_next) G_LOAD(Agn, Bgn, 0, ra0, rb0);
;       G_COMPUTE(0);
;       __syncthreads();
;       if (!last || has_next) G_WRITE(0, ra0, rb0);
;       if (!last) G_LOAD(Ag, Bg, kt + 3, ra0, rb0); else if (has_next) G_LOAD(Agn, Bgn, 1, ra0, rb0);
;       G_COMPUTE(1);
;       __syncthreads();
	s_waitcnt vmcnt(6)
	ds_write_b128 v202, v[130:133]
	s_waitcnt vmcnt(5)
	ds_write_b128 v203, v[176:179]
	ds_write_b128 v202, v[236:239] offset:8192
	s_waitcnt vmcnt(4)
	ds_write_b128 v203, v[180:183] offset:8192
	s_waitcnt vmcnt(2)
	ds_write_b128 v202, v[134:137] offset:16384
	s_waitcnt vmcnt(1)
	ds_write_b128 v203, v[188:191] offset:16384
	ds_write_b128 v202, v[184:187] offset:24576
	s_waitcnt vmcnt(0)
	ds_write_b128 v203, v[240:243] offset:24576
	ds_read_b128 v[130:133], v205 offset:32768
	ds_read_b128 v[134:137], v204
	ds_read_b128 v[138:141], v204 offset:4096
	ds_read_b128 v[148:151], v205 offset:36864
	v_mfma_f32_32x32x16_bf16 v[2:17], v[172:175], v[152:155], v[2:17]
	s_waitcnt lgkmcnt(2)
	v_mfma_f32_32x32x16_bf16 v[114:129], v[130:133], v[134:137], v[114:129]
	s_waitcnt lgkmcnt(1)
	v_mfma_f32_32x32x16_bf16 v[50:65], v[130:133], v[138:141], v[50:65]
	s_waitcnt lgkmcnt(0)
	v_mfma_f32_32x32x16_bf16 v[98:113], v[148:151], v[134:137], v[98:113]
	v_mfma_f32_32x32x16_bf16 v[34:49], v[148:151], v[138:141], v[34:49]
	ds_read_b128 v[130:133], v205 offset:40960
	ds_read_b128 v[148:151], v205 offset:45056
	s_waitcnt lgkmcnt(1)
	v_mfma_f32_32x32x16_bf16 v[82:97], v[130:133], v[134:137], v[82:97]
	v_mfma_f32_32x32x16_bf16 v[18:33], v[130:133], v[138:141], v[18:33]
	s_waitcnt lgkmcnt(0)
	v_mfma_f32_32x32x16_bf16 v[66:81], v[148:151], v[134:137], v[66:81]
	v_mfma_f32_32x32x16_bf16 v[2:17], v[148:151], v[138:141], v[2:17]
	ds_read_b128 v[130:133], v207 offset:32768
	ds_read_b128 v[134:137], v206
	ds_read_b128 v[138:141], v206 offset:4096
	ds_read_b128 v[148:151], v207 offset:36864
	s_waitcnt lgkmcnt(2)
	v_mfma_f32_32x32x16_bf16 v[114:129], v[130:133], v[134:137], v[114:129]
	s_waitcnt lgkmcnt(1)
	v_mfma_f32_32x32x16_bf16 v[50:65], v[130:133], v[138:141], v[50:65]
	s_waitcnt lgkmcnt(0)
	v_mfma_f32_32x32x16_bf16 v[98:113], v[148:151], v[134:137], v[98:113]
	v_mfma_f32_32x32x16_bf16 v[34:49], v[148:151], v[138:141], v[34:49]
	ds_read_b128 v[130:133], v207 offset:40960
	ds_read_b128 v[148:151], v207 offset:45056
	s_waitcnt lgkmcnt(1)
	v_mfma_f32_32x32x16_bf16 v[82:97], v[130:133], v[134:137], v[82:97]
	v_mfma_f32_32x32x16_bf16 v[18:33], v[130:133], v[138:141], v[18:33]
	s_waitcnt lgkmcnt(0)
	v_mfma_f32_32x32x16_bf16 v[66:81], v[148:151], v[134:137], v[66:81]
	v_mfma_f32_32x32x16_bf16 v[2:17], v[148:151], v[138:141], v[2:17]
	ds_read_b128 v[130:133], v209 offset:32768
	ds_read_b128 v[134:137], v208
	ds_read_b128 v[138:141], v208 offset:4096
	ds_read_b128 v[148:151], v209 offset:36864
	s_waitcnt lgkmcnt(2)
	v_mfma_f32_32x32x16_bf16 v[114:129], v[130:133], v[134:137], v[114:129]
	s_waitcnt lgkmcnt(1)
	v_mfma_f32_32x32x16_bf16 v[50:65], v[130:133], v[138:141], v[50:65]
	s_waitcnt lgkmcnt(0)
	v_mfma_f32_32x32x16_bf16 v[98:113], v[148:151], v[134:137], v[98:113]
	v_mfma_f32_32x32x16_bf16 v[34:49], v[148:151], v[138:141], v[34:49]
	ds_read_b128 v[130:133], v209 offset:40960
	ds_read_b128 v[148:151], v209 offset:45056
	s_waitcnt lgkmcnt(1)
	v_mfma_f32_32x32x16_bf16 v[82:97], v[130:133], v[134:137], v[82:97]
	v_mfma_f32_32x32x16_bf16 v[18:33], v[130:133], v[138:141], v[18:33]
	s_waitcnt lgkmcnt(0)
	v_mfma_f32_32x32x16_bf16 v[66:81], v[148:151], v[134:137], v[66:81]
	v_mfma_f32_32x32x16_bf16 v[2:17], v[148:151], v[138:141], v[2:17]
	ds_read_b128 v[130:133], v211 offset:32768
	ds_read_b128 v[150:153], v210
	ds_read_b128 v[172:175], v210 offset:4096
	ds_read_b128 v[134:137], v211 offset:36864
	ds_read_b128 v[180:183], v211 offset:45056
	global_load_dwordx4 v[176:179], v[170:171], off offset:2048
	s_waitcnt lgkmcnt(3)
	v_mfma_f32_32x32x16_bf16 v[114:129], v[130:133], v[150:153], v[114:129]
	s_waitcnt lgkmcnt(2)
	v_mfma_f32_32x32x16_bf16 v[50:65], v[130:133], v[172:175], v[50:65]
	ds_read_b128 v[130:133], v211 offset:40960
	s_waitcnt lgkmcnt(2)
	v_mfma_f32_32x32x16_bf16 v[98:113], v[134:137], v[150:153], v[98:113]
	v_mfma_f32_32x32x16_bf16 v[34:49], v[134:137], v[172:175], v[34:49]
	v_add_co_u32_e32 v134, vcc, s35, v168
	s_nop 1
	v_addc_co_u32_e32 v135, vcc, 0, v169, vcc
	v_add_co_u32_e32 v138, vcc, s0, v168
	s_mov_b32 s0, 0xf1000
	s_nop 0
	v_addc_co_u32_e32 v139, vcc, 0, v169, vcc
	v_add_co_u32_e32 v148, vcc, s0, v168
	s_mov_b32 s0, 0x169000
	s_nop 0
	v_addc_co_u32_e32 v149, vcc, 0, v169, vcc
	v_add_co_u32_e32 v154, vcc, s0, v168
	s_waitcnt lgkmcnt(0)
	v_mfma_f32_32x32x16_bf16 v[82:97], v[130:133], v[150:153], v[82:97]
	global_load_dwordx4 v[184:187], v[134:135], off offset:512
	global_load_dwordx4 v[188:191], v[138:139], off offset:512
	v_addc_co_u32_e32 v155, vcc, 0, v169, vcc
	v_mad_i64_i32 v[168:169], s[0:1], v0, s13, v[162:163]
	s_movk_i32 s0, 0xa00
	v_cndmask_b32_e64 v0, 0, 1, s[4:5]
	v_mfma_f32_32x32x16_bf16 v[18:33], v[130:133], v[172:175], v[18:33]
	global_load_dwordx4 v[130:133], v[142:143], off offset:2048
	global_load_dwordx4 v[192:195], v[146:147], off offset:2048
	global_load_dwordx4 v[196:199], v[148:149], off offset:512
	global_load_dwordx4 v[230:233], v[154:155], off offset:512
	s_andn2_b64 vcc, exec, s[4:5]
	v_mfma_f32_32x32x16_bf16 v[66:81], v[180:183], v[150:153], v[66:81]
	global_load_dwordx4 v[150:153], v[158:159], off offset:2048
	s_barrier
; #define G_LOAD(AG, BG, kt, RA, RB) do { const int k0_ = (kt) * 64; int ac_ = k0_; if (g.remap) ac_ = k0_ < 512 ? k0_ : (k0_ < 1024 ? g.seg2 + k0_ - 512 : 2304 + k0_ - 1024); \
;     _Pragma("unroll") for (int i = 0; i < 4; ++i) { RA[i] = *(const u32x4*)(AG + (size_t)(64 * i) * g.lda + ac_); RB[i] = *(const u32x4*)(BG + (size_t)(64 * i) * g.K + k0_); } } while (0)
; #define G_WRITE(buf, RA, RB) do { _Pragma("unroll") for (int i = 0; i < 4; ++i) { *(u32x4*)(lds + (buf) * 65536 + i * 8192 + soff) = RA[i]; *(u32x4*)(lds + (buf) * 65536 + 32768 + i * 8192 + soff) = RB[i]; } } while (0)
; template <int EPI>
; DI void gemm_phase(char* lds, const Params& p, const GemmDesc g, int layer) {
;     ...
;       const bool last = kt + 2 >= nk;
;       G_WRITE(1, ra0, rb0);
;       if (!last) G_LOAD(Ag, Bg, kt + 2, ra0, rb0); else if (has_next) G_LOAD(Agn, Bgn, 0, ra0, rb0);
;       G_COMPUTE(0);
;       __syncthreads();
;       if (!last || has_next) G_WRITE(0, ra0, rb0);
;       if (!last) G_LOAD(Ag, Bg, kt + 3, ra0, rb0); else if (has_next) G_LOAD(Agn, Bgn, 1, ra0, rb0);
;       G_COMPUTE(1);
;       __syncthreads();
	s_waitcnt vmcnt(6)
	ds_write_b128 v201, v[184:187]
	ds_write_b128 v201, v[176:179] offset:32768
	s_waitcnt vmcnt(5)
	ds_write_b128 v201, v[188:191] offset:8192
	s_waitcnt vmcnt(4)
	ds_write_b128 v201, v[130:133] offset:40960
	s_waitcnt vmcnt(2)
	ds_write_b128 v201, v[196:199] offset:16384
	ds_write_b128 v201, v[192:195] offset:49152
	s_waitcnt vmcnt(1)
	ds_write_b128 v201, v[230:233] offset:24576
	s_waitcnt vmcnt(0)
	ds_write_b128 v201, v[150:153] offset:57344
	global_load_dwordx4 v[236:239], v[138:139], off offset:640
	global_load_dwordx4 v[240:243], v[134:135], off offset:640
	global_load_dwordx4 v[184:187], v[170:171], off offset:2176
	global_load_dwordx4 v[188:191], v[142:143], off offset:2176
	global_load_dwordx4 v[192:195], v[154:155], off offset:640
	global_load_dwordx4 v[196:199], v[148:149], off offset:640
	global_load_dwordx4 v[230:233], v[146:147], off offset:2176
	global_load_dwordx4 v[244:247], v[158:159], off offset:2176
	v_mfma_f32_32x32x16_bf16 v[2:17], v[180:183], v[172:175], v[2:17]
	ds_read_b128 v[130:133], v223
	ds_read_b128 v[150:153], v222
	ds_read_b128 v[172:175], v222 offset:4096
	ds_read_b128 v[176:179], v223 offset:4096
	s_waitcnt lgkmcnt(2)
	v_mfma_f32_32x32x16_bf16 v[114:129], v[130:133], v[150:153], v[114:129]
	s_waitcnt lgkmcnt(1)
	v_mfma_f32_32x32x16_bf16 v[50:65], v[130:133], v[172:175], v[50:65]
	s_waitcnt lgkmcnt(0)
	v_mfma_f32_32x32x16_bf16 v[98:113], v[176:179], v[150:153], v[98:113]
	v_mfma_f32_32x32x16_bf16 v[34:49], v[176:179], v[172:175], v[34:49]
	ds_read_b128 v[130:133], v223 offset:8192
	ds_read_b128 v[176:179], v223 offset:12288
	s_waitcnt lgkmcnt(1)
	v_mfma_f32_32x32x16_bf16 v[82:97], v[130:133], v[150:153], v[82:97]
	v_mfma_f32_32x32x16_bf16 v[18:33], v[130:133], v[172:175], v[18:33]
	s_waitcnt lgkmcnt(0)
	v_mfma_f32_32x32x16_bf16 v[66:81], v[176:179], v[150:153], v[66:81]
	v_mfma_f32_32x32x16_bf16 v[2:17], v[176:179], v[172:175], v[2:17]
	ds_read_b128 v[130:133], v225
	ds_read_b128 v[150:153], v224
	ds_read_b128 v[172:175], v224 offset:4096
	ds_read_b128 v[176:179], v225 offset:4096
	s_waitcnt lgkmcnt(2)
	v_mfma_f32_32x32x16_bf16 v[114:129], v[130:133], v[150:153], v[114:129]
	s_waitcnt lgkmcnt(1)
	v_mfma_f32_32x32x16_bf16 v[50:65], v[130:133], v[172:175], v[50:65]
	s_waitcnt lgkmcnt(0)
	v_mfma_f32_32x32x16_bf16 v[98:113], v[176:179], v[150:153], v[98:113]
	v_mfma_f32_32x32x16_bf16 v[34:49], v[176:179], v[172:175], v[34:49]
	ds_read_b128 v[130:133], v225 offset:8192
	ds_read_b128 v[176:179], v225 offset:12288
	s_waitcnt lgkmcnt(1)
	v_mfma_f32_32x32x16_bf16 v[82:97], v[130:133], v[150:153], v[82:97]
	v_mfma_f32_32x32x16_bf16 v[18:33], v[130:133], v[172:175], v[18:33]
	s_waitcnt lgkmcnt(0)
	v_mfma_f32_32x32x16_bf16 v[66:81], v[176:179], v[150:153], v[66:81]
	v_mfma_f32_32x32x16_bf16 v[2:17], v[176:179], v[172:175], v[2:17]
	ds_read_b128 v[130:133], v227
	ds_read_b128 v[150:153], v226
	ds_read_b128 v[172:175], v226 offset:4096
	ds_read_b128 v[176:179], v227 offset:4096
	s_waitcnt lgkmcnt(2)
	v_mfma_f32_32x32x16_bf16 v[114:129], v[130:133], v[150:153], v[114:129]
	s_waitcnt lgkmcnt(1)
	v_mfma_f32_32x32x16_bf16 v[50:65], v[130:133], v[172:175], v[50:65]
	s_waitcnt lgkmcnt(0)
	v_mfma_f32_32x32x16_bf16 v[98:113], v[176:179], v[150:153], v[98:113]
	v_mfma_f32_32x32x16_bf16 v[34:49], v[176:179], v[172:175], v[34:49]
	ds_read_b128 v[130:133], v227 offset:8192
	ds_read_b128 v[176:179], v227 offset:12288
	s_waitcnt lgkmcnt(1)
	v_mfma_f32_32x32x16_bf16 v[82:97], v[130:133], v[150:153], v[82:97]
	v_mfma_f32_32x32x16_bf16 v[18:33], v[130:133], v[172:175], v[18:33]
	s_waitcnt lgkmcnt(0)
	v_mfma_f32_32x32x16_bf16 v[66:81], v[176:179], v[150:153], v[66:81]
	v_mfma_f32_32x32x16_bf16 v[2:17], v[176:179], v[172:175], v[2:17]
	ds_read_b128 v[130:133], v229
	ds_read_b128 v[150:153], v228
	ds_read_b128 v[172:175], v228 offset:4096
	ds_read_b128 v[176:179], v229 offset:4096
	s_waitcnt lgkmcnt(2)
	v_mfma_f32_32x32x16_bf16 v[114:129], v[130:133], v[150:153], v[114:129]
	s_waitcnt lgkmcnt(1)
	v_mfma_f32_32x32x16_bf16 v[50:65], v[130:133], v[172:175], v[50:65]
	s_waitcnt lgkmcnt(0)
	v_mfma_f32_32x32x16_bf16 v[98:113], v[176:179], v[150:153], v[98:113]
	v_mfma_f32_32x32x16_bf16 v[34:49], v[176:179], v[172:175], v[34:49]
	ds_read_b128 v[130:133], v229 offset:8192
	ds_read_b128 v[176:179], v229 offset:12288
	s_waitcnt lgkmcnt(1)
	v_mfma_f32_32x32x16_bf16 v[82:97], v[130:133], v[150:153], v[82:97]
	v_mfma_f32_32x32x16_bf16 v[18:33], v[130:133], v[172:175], v[18:33]
	s_waitcnt lgkmcnt(0)
	v_mfma_f32_32x32x16_bf16 v[66:81], v[176:179], v[150:153], v[66:81]
	s_barrier
; #define G_LOAD(AG, BG, kt, RA, RB) do { const int k0_ = (kt) * 64; int ac_ = k0_; if (g.remap) ac_ = k0_ < 512 ? k0_ : (k0_ < 1024 ? g.seg2 + k0_ - 512 : 2304 + k0_ - 1024); \
;     _Pragma("unroll") for (int i = 0; i < 4; ++i) { RA[i] = *(const u32x4*)(AG + (size_t)(64 * i) * g.lda + ac_); RB[i] = *(const u32x4*)(BG + (size_t)(64 * i) * g.K + k0_); } } while (0)
; #define G_WRITE(buf, RA, RB) do { _Pragma("unroll") for (int i = 0; i < 4; ++i) { *(u32x4*)(lds + (buf) * 65536 + i * 8192 + soff) = RA[i]; *(u32x4*)(lds + (buf) * 65536 + 32768 + i * 8192 + soff) = RB[i]; } } while (0)
; template <int EPI>
; DI void gemm_phase(char* lds, const Params& p, const GemmDesc g, int layer) {
;     ...
;       const bool last = kt + 2 >= nk;
;       G_WRITE(1, ra0, rb0);
;       if (!last) G_LOAD(Ag, Bg, kt + 2, ra0, rb0); else if (has_next) G_LOAD(Agn, Bgn, 0, ra0, rb0);
;       G_COMPUTE(0);
;       __syncthreads();
;       if (!last || has_next) G_WRITE(0, ra0, rb0);
;       if (!last) G_LOAD(Ag, Bg, kt + 3, ra0, rb0); else if (has_next) G_LOAD(Agn, Bgn, 1, ra0, rb0);
;       G_COMPUTE(1);
;       __syncthreads();
	s_waitcnt vmcnt(6)
	ds_write_b128 v202, v[240:243]
	s_waitcnt vmcnt(5)
	ds_write_b128 v203, v[184:187]
	ds_write_b128 v202, v[236:239] offset:8192
	s_waitcnt vmcnt(4)
	ds_write_b128 v203, v[188:191] offset:8192
	s_waitcnt vmcnt(2)
	ds_write_b128 v202, v[196:199] offset:16384
	s_waitcnt vmcnt(1)
	ds_write_b128 v203, v[230:233] offset:16384
	ds_write_b128 v202, v[192:195] offset:24576
	s_waitcnt vmcnt(0)
	ds_write_b128 v203, v[244:247] offset:24576
	global_load_dwordx4 v[236:239], v[170:171], off offset:2304
	global_load_dwordx4 v[180:183], v[134:135], off offset:768
	global_load_dwordx4 v[184:187], v[138:139], off offset:768
	global_load_dwordx4 v[188:191], v[142:143], off offset:2304
	global_load_dwordx4 v[192:195], v[146:147], off offset:2304
	global_load_dwordx4 v[196:199], v[148:149], off offset:768
	global_load_dwordx4 v[230:233], v[154:155], off offset:768
	global_load_dwordx4 v[240:243], v[158:159], off offset:2304
	v_mfma_f32_32x32x16_bf16 v[2:17], v[176:179], v[172:175], v[2:17]
	ds_read_b128 v[130:133], v205 offset:32768
	ds_read_b128 v[150:153], v204
	ds_read_b128 v[172:175], v204 offset:4096
	ds_read_b128 v[176:179], v205 offset:36864
	s_waitcnt lgkmcnt(2)
	v_mfma_f32_32x32x16_bf16 v[114:129], v[130:133], v[150:153], v[114:129]
	s_waitcnt lgkmcnt(1)
	v_mfma_f32_32x32x16_bf16 v[50:65], v[130:133], v[172:175], v[50:65]
	s_waitcnt lgkmcnt(0)
	v_mfma_f32_32x32x16_bf16 v[98:113], v[176:179], v[150:153], v[98:113]
	v_mfma_f32_32x32x16_bf16 v[34:49], v[176:179], v[172:175], v[34:49]
	ds_read_b128 v[130:133], v205 offset:40960
	ds_read_b128 v[176:179], v205 offset:45056
	s_waitcnt lgkmcnt(1)
	v_mfma_f32_32x32x16_bf16 v[82:97], v[130:133], v[150:153], v[82:97]
	v_mfma_f32_32x32x16_bf16 v[18:33], v[130:133], v[172:175], v[18:33]
	s_waitcnt lgkmcnt(0)
	v_mfma_f32_32x32x16_bf16 v[66:81], v[176:179], v[150:153], v[66:81]
	v_mfma_f32_32x32x16_bf16 v[2:17], v[176:179], v[172:175], v[2:17]
	ds_read_b128 v[130:133], v207 offset:32768
	ds_read_b128 v[150:153], v206
	ds_read_b128 v[172:175], v206 offset:4096
	ds_read_b128 v[176:179], v207 offset:36864
	s_waitcnt lgkmcnt(2)
	v_mfma_f32_32x32x16_bf16 v[114:129], v[130:133], v[150:153], v[114:129]
	s_waitcnt lgkmcnt(1)
	v_mfma_f32_32x32x16_bf16 v[50:65], v[130:133], v[172:175], v[50:65]
	s_waitcnt lgkmcnt(0)
	v_mfma_f32_32x32x16_bf16 v[98:113], v[176:179], v[150:153], v[98:113]
	v_mfma_f32_32x32x16_bf16 v[34:49], v[176:179], v[172:175], v[34:49]
	ds_read_b128 v[130:133], v207 offset:40960
	ds_read_b128 v[176:179], v207 offset:45056
	s_waitcnt lgkmcnt(1)
	v_mfma_f32_32x32x16_bf16 v[82:97], v[130:133], v[150:153], v[82:97]
	v_mfma_f32_32x32x16_bf16 v[18:33], v[130:133], v[172:175], v[18:33]
	s_waitcnt lgkmcnt(0)
	v_mfma_f32_32x32x16_bf16 v[66:81], v[176:179], v[150:153], v[66:81]
	v_mfma_f32_32x32x16_bf16 v[2:17], v[176:179], v[172:175], v[2:17]
	ds_read_b128 v[130:133], v209 offset:32768
	ds_read_b128 v[150:153], v208
	ds_read_b128 v[172:175], v208 offset:4096
	ds_read_b128 v[176:179], v209 offset:36864
	s_waitcnt lgkmcnt(2)
	v_mfma_f32_32x32x16_bf16 v[114:129], v[130:133], v[150:153], v[114:129]
	s_waitcnt lgkmcnt(1)
	v_mfma_f32_32x32x16_bf16 v[50:65], v[130:133], v[172:175], v[50:65]
	s_waitcnt lgkmcnt(0)
	v_mfma_f32_32x32x16_bf16 v[98:113], v[176:179], v[150:153], v[98:113]
	v_mfma_f32_32x32x16_bf16 v[34:49], v[176:179], v[172:175], v[34:49]
	ds_read_b128 v[130:133], v209 offset:40960
	ds_read_b128 v[176:179], v209 offset:45056
	s_waitcnt lgkmcnt(1)
	v_mfma_f32_32x32x16_bf16 v[82:97], v[130:133], v[150:153], v[82:97]
	v_mfma_f32_32x32x16_bf16 v[18:33], v[130:133], v[172:175], v[18:33]
	s_waitcnt lgkmcnt(0)
	v_mfma_f32_32x32x16_bf16 v[66:81], v[176:179], v[150:153], v[66:81]
	v_mfma_f32_32x32x16_bf16 v[2:17], v[176:179], v[172:175], v[2:17]
	ds_read_b128 v[130:133], v211 offset:32768
	ds_read_b128 v[150:153], v210
	ds_read_b128 v[172:175], v210 offset:4096
	ds_read_b128 v[176:179], v211 offset:36864
	s_waitcnt lgkmcnt(2)
	v_mfma_f32_32x32x16_bf16 v[114:129], v[130:133], v[150:153], v[114:129]
	s_waitcnt lgkmcnt(1)
	v_mfma_f32_32x32x16_bf16 v[50:65], v[130:133], v[172:175], v[50:65]
	s_waitcnt lgkmcnt(0)
	v_mfma_f32_32x32x16_bf16 v[98:113], v[176:179], v[150:153], v[98:113]
	v_mfma_f32_32x32x16_bf16 v[34:49], v[176:179], v[172:175], v[34:49]
	ds_read_b128 v[130:133], v211 offset:40960
	ds_read_b128 v[176:179], v211 offset:45056
	s_waitcnt lgkmcnt(1)
	v_mfma_f32_32x32x16_bf16 v[82:97], v[130:133], v[150:153], v[82:97]
	v_mfma_f32_32x32x16_bf16 v[18:33], v[130:133], v[172:175], v[18:33]
	s_waitcnt lgkmcnt(0)
	v_mfma_f32_32x32x16_bf16 v[66:81], v[176:179], v[150:153], v[66:81]
	s_barrier
; #define G_LOAD(AG, BG, kt, RA, RB) do { const int k0_ = (kt) * 64; int ac_ = k0_; if (g.remap) ac_ = k0_ < 512 ? k0_ : (k0_ < 1024 ? g.seg2 + k0_ - 512 : 2304 + k0_ - 1024); \
;     _Pragma("unroll") for (int i = 0; i < 4; ++i) { RA[i] = *(const u32x4*)(AG + (size_t)(64 * i) * g.lda + ac_); RB[i] = *(const u32x4*)(BG + (size_t)(64 * i) * g.K + k0_); } } while (0)
; #define G_WRITE(buf, RA, RB) do { _Pragma("unroll") for (int i = 0; i < 4; ++i) { *(u32x4*)(lds + (buf) * 65536 + i * 8192 + soff) = RA[i]; *(u32x4*)(lds + (buf) * 65536 + 32768 + i * 8192 + soff) = RB[i]; } } while (0)
; template <int EPI>
; DI void gemm_phase(char* lds, const Params& p, const GemmDesc g, int layer) {
;     ...
;       const bool last = kt + 2 >= nk;
;       G_WRITE(1, ra0, rb0);
;       if (!last) G_LOAD(Ag, Bg, kt + 2, ra0, rb0); else if (has_next) G_LOAD(Agn, Bgn, 0, ra0, rb0);
;       G_COMPUTE(0);
;       __syncthreads();
;       if (!last || has_next) G_WRITE(0, ra0, rb0);
;       if (!last) G_LOAD(Ag, Bg, kt + 3, ra0, rb0); else if (has_next) G_LOAD(Agn, Bgn, 1, ra0, rb0);
;       G_COMPUTE(1);
;       __syncthreads();
	s_waitcnt vmcnt(6)
	ds_write_b128 v201, v[180:183]
	ds_write_b128 v201, v[236:239] offset:32768
	s_waitcnt vmcnt(5)
	ds_write_b128 v201, v[184:187] offset:8192
	s_waitcnt vmcnt(4)
	ds_write_b128 v201, v[188:191] offset:40960
	s_waitcnt vmcnt(2)
	ds_write_b128 v201, v[196:199] offset:16384
	ds_write_b128 v201, v[192:195] offset:49152
	s_waitcnt vmcnt(1)
	ds_write_b128 v201, v[230:233] offset:24576
	s_waitcnt vmcnt(0)
	ds_write_b128 v201, v[240:243] offset:57344
	global_load_dwordx4 v[236:239], v[170:171], off offset:2432
	global_load_dwordx4 v[134:137], v[134:135], off offset:896
	global_load_dwordx4 v[138:141], v[138:139], off offset:896
	global_load_dwordx4 v[142:145], v[142:143], off offset:2432
	global_load_dwordx4 v[240:243], v[146:147], off offset:2432
	global_load_dwordx4 v[146:149], v[148:149], off offset:896
	global_load_dwordx4 v[154:157], v[154:155], off offset:896
	global_load_dwordx4 v[158:161], v[158:159], off offset:2432
	v_mfma_f32_32x32x16_bf16 v[2:17], v[176:179], v[172:175], v[2:17]
	ds_read_b128 v[130:133], v223
	ds_read_b128 v[150:153], v222
	ds_read_b128 v[172:175], v222 offset:4096
	ds_read_b128 v[176:179], v223 offset:4096
	s_waitcnt lgkmcnt(2)
	v_mfma_f32_32x32x16_bf16 v[114:129], v[130:133], v[150:153], v[114:129]
	s_waitcnt lgkmcnt(1)
	v_mfma_f32_32x32x16_bf16 v[50:65], v[130:133], v[172:175], v[50:65]
	s_waitcnt lgkmcnt(0)
	v_mfma_f32_32x32x16_bf16 v[98:113], v[176:179], v[150:153], v[98:113]
	v_mfma_f32_32x32x16_bf16 v[34:49], v[176:179], v[172:175], v[34:49]
	ds_read_b128 v[130:133], v223 offset:8192
	ds_read_b128 v[176:179], v223 offset:12288
	s_waitcnt lgkmcnt(1)
	v_mfma_f32_32x32x16_bf16 v[82:97], v[130:133], v[150:153], v[82:97]
	v_mfma_f32_32x32x16_bf16 v[18:33], v[130:133], v[172:175], v[18:33]
	s_waitcnt lgkmcnt(0)
	v_mfma_f32_32x32x16_bf16 v[66:81], v[176:179], v[150:153], v[66:81]
	v_mfma_f32_32x32x16_bf16 v[2:17], v[176:179], v[172:175], v[2:17]
	ds_read_b128 v[130:133], v225
	ds_read_b128 v[150:153], v224
	ds_read_b128 v[172:175], v224 offset:4096
	ds_read_b128 v[176:179], v225 offset:4096
	s_waitcnt lgkmcnt(2)
	v_mfma_f32_32x32x16_bf16 v[114:129], v[130:133], v[150:153], v[114:129]
	s_waitcnt lgkmcnt(1)
	v_mfma_f32_32x32x16_bf16 v[50:65], v[130:133], v[172:175], v[50:65]
	s_waitcnt lgkmcnt(0)
	v_mfma_f32_32x32x16_bf16 v[98:113], v[176:179], v[150:153], v[98:113]
	v_mfma_f32_32x32x16_bf16 v[34:49], v[176:179], v[172:175], v[34:49]
	ds_read_b128 v[130:133], v225 offset:8192
	ds_read_b128 v[176:179], v225 offset:12288
	s_waitcnt lgkmcnt(1)
	v_mfma_f32_32x32x16_bf16 v[82:97], v[130:133], v[150:153], v[82:97]
	v_mfma_f32_32x32x16_bf16 v[18:33], v[130:133], v[172:175], v[18:33]
	s_waitcnt lgkmcnt(0)
	v_mfma_f32_32x32x16_bf16 v[66:81], v[176:179], v[150:153], v[66:81]
	v_mfma_f32_32x32x16_bf16 v[2:17], v[176:179], v[172:175], v[2:17]
	ds_read_b128 v[130:133], v227
	ds_read_b128 v[150:153], v226
	ds_read_b128 v[172:175], v226 offset:4096
	ds_read_b128 v[176:179], v227 offset:4096
	s_waitcnt lgkmcnt(2)
	v_mfma_f32_32x32x16_bf16 v[114:129], v[130:133], v[150:153], v[114:129]
	s_waitcnt lgkmcnt(1)
	v_mfma_f32_32x32x16_bf16 v[50:65], v[130:133], v[172:175], v[50:65]
	s_waitcnt lgkmcnt(0)
	v_mfma_f32_32x32x16_bf16 v[98:113], v[176:179], v[150:153], v[98:113]
	v_mfma_f32_32x32x16_bf16 v[34:49], v[176:179], v[172:175], v[34:49]
	ds_read_b128 v[130:133], v227 offset:8192
	ds_read_b128 v[176:179], v227 offset:12288
	s_waitcnt lgkmcnt(1)
	v_mfma_f32_32x32x16_bf16 v[82:97], v[130:133], v[150:153], v[82:97]
	v_mfma_f32_32x32x16_bf16 v[18:33], v[130:133], v[172:175], v[18:33]
	s_waitcnt lgkmcnt(0)
	v_mfma_f32_32x32x16_bf16 v[66:81], v[176:179], v[150:153], v[66:81]
	v_mfma_f32_32x32x16_bf16 v[2:17], v[176:179], v[172:175], v[2:17]
	ds_read_b128 v[130:133], v229
	ds_read_b128 v[172:175], v228
	ds_read_b128 v[176:179], v228 offset:4096
	ds_read_b128 v[150:153], v229 offset:4096
	ds_read_b128 v[180:183], v229 offset:8192
	s_waitcnt lgkmcnt(3)
	v_mfma_f32_32x32x16_bf16 v[114:129], v[130:133], v[172:175], v[114:129]
	s_waitcnt lgkmcnt(2)
	v_mfma_f32_32x32x16_bf16 v[50:65], v[130:133], v[176:179], v[50:65]
	v_lshl_add_u32 v170, s75, 8, v200
	v_mad_i64_i32 v[170:171], s[0:1], v170, s0, v[164:165]
	v_cmp_ne_u32_e64 s[0:1], 1, v0
	s_waitcnt lgkmcnt(1)
	v_mfma_f32_32x32x16_bf16 v[98:113], v[150:153], v[172:175], v[98:113]
	v_mfma_f32_32x32x16_bf16 v[34:49], v[150:153], v[176:179], v[34:49]
	s_nop 0
	s_nop 0
	s_nop 0
	s_nop 0
	s_nop 0
	ds_read_b128 v[184:187], v229 offset:12288
	s_waitcnt lgkmcnt(0)
	s_barrier
	s_waitcnt vmcnt(6)
	ds_write_b128 v202, v[134:137]
	ds_write_b128 v203, v[236:239]
	s_waitcnt vmcnt(5)
	ds_write_b128 v202, v[138:141] offset:8192
	v_mfma_f32_32x32x16_bf16 v[82:97], v[180:183], v[172:175], v[82:97]
	s_waitcnt vmcnt(4)
	ds_write_b128 v203, v[142:145] offset:8192
	s_waitcnt vmcnt(2)
	ds_write_b128 v202, v[146:149] offset:16384
	ds_write_b128 v203, v[240:243] offset:16384
	s_waitcnt vmcnt(1)
	ds_write_b128 v202, v[154:157] offset:24576
	s_waitcnt vmcnt(0)
	ds_write_b128 v203, v[158:161] offset:24576
	v_mfma_f32_32x32x16_bf16 v[18:33], v[180:183], v[176:179], v[18:33]
	v_mfma_f32_32x32x16_bf16 v[66:81], v[184:187], v[172:175], v[66:81]
	v_mfma_f32_32x32x16_bf16 v[2:17], v[184:187], v[176:179], v[2:17]
	s_cbranch_vccnz .LBB0_120
	v_add_co_u32_e32 v138, vcc, 0x78000, v168
	global_load_dwordx4 v[134:137], v[168:169], off
	global_load_dwordx4 v[130:133], v[170:171], off
	v_addc_co_u32_e32 v139, vcc, 0, v169, vcc
	v_add_co_u32_e32 v142, vcc, 0x28000, v170
	global_load_dwordx4 v[138:141], v[138:139], off
	s_nop 0
	v_addc_co_u32_e32 v143, vcc, 0, v171, vcc
	v_add_co_u32_e32 v146, vcc, 0xf0000, v168
	global_load_dwordx4 v[142:145], v[142:143], off
	s_nop 0
	v_addc_co_u32_e32 v147, vcc, 0, v169, vcc
	v_add_co_u32_e32 v150, vcc, 0x50000, v170
	global_load_dwordx4 v[146:149], v[146:147], off
	s_nop 0
	v_addc_co_u32_e32 v151, vcc, 0, v171, vcc
	v_add_co_u32_e32 v154, vcc, 0x168000, v168
	global_load_dwordx4 v[150:153], v[150:151], off
	s_nop 0
	v_addc_co_u32_e32 v155, vcc, 0, v169, vcc
	v_add_co_u32_e32 v158, vcc, 0x78000, v170
	global_load_dwordx4 v[154:157], v[154:155], off
	s_nop 0
	v_addc_co_u32_e32 v159, vcc, 0, v171, vcc
	global_load_dwordx4 v[158:161], v[158:159], off
